# RWKV scan waves: per-chunk ring offsets and output pointers kept incrementally (17 fewer chunk-top instructions)
# baseline (speedup 1.0000x reference)
; #define LAS __attribute__((address_space(3)))
; __device__ __forceinline__ void rwkv_scan_unit(LAS unsigned char* lds, const float* Wd, const float* V, const bf16_t* RKKB, float* Yraw, int p, int rg, int tid) {
;     const int lane = tid & 63, wave = __builtin_amdgcn_readfirstlane(tid >> 6);
;     constexpr int NCH = SEQ / SCAN_CH;
;     scan_load_chunk(lds + (tid >> 8) * SCAN_SLOT_B, Wd, V, RKKB, p, rg, (tid >> 8) * SCAN_CH, tid & 255);
;     __syncthreads();
;     f32x4 S = (f32x4){0.f, 0.f, 0.f, 0.f};
;     const int kq = lane & 15, rl = wave * 4 + (lane >> 4);
;     for (int c = 0; c < NCH; ++c) {
;         if (wave >= 4) { if (c + 2 < NCH) scan_load_chunk(lds + ((c + 2) % 3) * SCAN_SLOT_B, Wd, V, RKKB, p, rg, (c + 2) * SCAN_CH, tid - 256); }
;         else {
;             LAS const unsigned char* sl = lds + (c % 3) * SCAN_SLOT_B + kq * 16;
;             LAS const unsigned char* vl = lds + (c % 3) * SCAN_SLOT_B + 1280 + rl * 4;
;             float* yo = Yraw + ((size_t)p * SEQ + c * SCAN_CH + kq) * 64 + rg * 16 + rl;
;             f32x4 w = *(LAS const f32x4*)(sl), b = *(LAS const f32x4*)(sl + 256), k = *(LAS const f32x4*)(sl + 512), kk = *(LAS const f32x4*)(sl + 768), r = *(LAS const f32x4*)(sl + 1024);
;             float v = *(LAS const float*)(vl); float yp[16];
.LBB0_340:
	s_or_b64 exec, exec, s[6:7]
	v_add3_u32 v14, v14, v10, v22
	s_waitcnt vmcnt(0)
	v_lshlrev_b32_e32 v10, 16, v2
	v_and_b32_e32 v11, 0xffff0000, v2
	v_lshlrev_b32_e32 v12, 16, v3
	v_and_b32_e32 v13, 0xffff0000, v3
	v_lshlrev_b32_e32 v2, 16, v4
	v_and_b32_e32 v3, 0xffff0000, v4
	v_lshlrev_b32_e32 v4, 16, v5
	v_and_b32_e32 v5, 0xffff0000, v5
	ds_write_b128 v14, v[10:13] offset:10752
	ds_write_b128 v14, v[2:5] offset:10768
	s_and_saveexec_b64 s[6:7], s[4:5]
	v_lshrrev_b32_e32 v2, 8, v232
	v_lshlrev_b32_e32 v2, 11, v2
	v_and_b32_e32 v3, 3, v232
	v_lshl_or_b32 v2, v3, 9, v2
	v_and_b32_e32 v3, 0xfc, v232
	v_or_b32_e32 v2, v2, v3
	v_add_u32_e32 v2, 0x1f800, v2
	ds_write_b32 v2, v6
	ds_write_b32 v2, v7 offset:128
	ds_write_b32 v2, v8 offset:256
	ds_write_b32 v2, v9 offset:384
	s_or_b64 exec, exec, s[6:7]
	v_and_b32_e32 v3, 4, v32
	v_cmp_eq_u32_e64 s[6:7], 0, v3
	v_and_b32_e32 v3, 1, v32
	s_ashr_i32 s4, s10, 6
	v_and_b32_e32 v4, 2, v32
	v_cmp_eq_u32_e64 s[10:11], 0, v3
	v_add_u32_e32 v3, 0xffffff00, v32
	v_add_u32_e32 v12, 0x100, v32
	v_add_u32_e32 v14, 0x200, v32
	s_cmp_lt_i32 s4, 4
	v_cmp_eq_u32_e64 s[8:9], 0, v4
	v_ashrrev_i32_e32 v4, 4, v3
	v_ashrrev_i32_e32 v6, 4, v32
	v_ashrrev_i32_e32 v8, 5, v3
	v_ashrrev_i32_e32 v10, 5, v32
	v_ashrrev_i32_e32 v12, 5, v12
	v_ashrrev_i32_e32 v14, 5, v14
	v_ashrrev_i32_e32 v16, 2, v3
	s_movk_i32 s19, 0x540
	s_cselect_b64 s[16:17], -1, 0
	v_mul_lo_u32 v74, v4, s19
	v_mul_lo_u32 v75, v6, s19
	v_mul_lo_u32 v77, v8, s19
	v_mul_lo_u32 v78, v10, s19
	v_mul_lo_u32 v79, v12, s19
	v_mul_lo_u32 v80, v14, s19
	v_mul_lo_u32 v81, v16, s19
	s_and_b32 s23, s20, 7
	s_ashr_i32 s19, s18, 31
	s_lshl_b32 s21, s23, 22
	s_lshl_b64 s[24:25], s[18:19], 20
	v_ashrrev_i32_e32 v17, 31, v16
	v_lshlrev_b32_e32 v19, 5, v32
	s_add_u32 s24, s21, s24
	v_and_b32_e32 v76, 0xe0, v19
	s_addc_u32 s25, 0, s25
	v_lshlrev_b64 v[16:17], 8, v[16:17]
	s_lshl_b32 s20, s20, 3
	v_and_b32_e32 v19, 3, v3
	v_lshl_add_u64 v[16:17], s[24:25], 0, v[16:17]
	s_and_b32 s26, s20, 0xc0
	v_lshlrev_b32_e32 v19, 4, v19
	v_readlane_b32 s20, v254, 47
	v_or3_b32 v16, v16, s26, v19
	v_readlane_b32 s21, v254, 48
	s_lshl_b32 s27, s23, 23
	v_ashrrev_i32_e32 v5, 31, v4
	v_lshl_add_u64 v[46:47], s[20:21], 0, v[16:17]
	s_lshl_b64 s[20:21], s[18:19], 21
	v_ashrrev_i32_e32 v7, 31, v6
	v_ashrrev_i32_e32 v9, 31, v8
	v_ashrrev_i32_e32 v11, 31, v10
	v_ashrrev_i32_e32 v13, 31, v12
	v_ashrrev_i32_e32 v15, 31, v14
	s_add_u32 s20, s27, s20
	v_lshlrev_b32_e32 v18, 4, v3
	s_addc_u32 s21, 0, s21
	v_lshlrev_b64 v[14:15], 9, v[14:15]
	v_lshlrev_b64 v[12:13], 9, v[12:13]
	v_lshlrev_b64 v[10:11], 9, v[10:11]
	v_lshlrev_b64 v[8:9], 9, v[8:9]
	v_lshlrev_b64 v[6:7], 8, v[6:7]
	v_lshlrev_b64 v[4:5], 8, v[4:5]
	v_and_b32_e32 v73, 0xf0, v18
	v_lshl_add_u64 v[14:15], s[20:21], 0, v[14:15]
	v_lshl_add_u64 v[12:13], s[20:21], 0, v[12:13]
	v_lshl_add_u64 v[10:11], s[20:21], 0, v[10:11]
	v_lshl_add_u64 v[8:9], s[20:21], 0, v[8:9]
	v_lshl_add_u64 v[6:7], s[24:25], 0, v[6:7]
	v_readlane_b32 s20, v254, 51
	v_lshl_add_u64 v[4:5], s[24:25], 0, v[4:5]
	v_or_b32_e32 v6, v6, v73
	v_readlane_b32 s21, v254, 52
	v_or_b32_e32 v4, v4, v73
	s_lshl_b64 s[18:19], s[18:19], 12
	v_lshl_add_u64 v[56:57], s[20:21], 0, v[6:7]
	v_lshl_add_u64 v[58:59], s[20:21], 0, v[4:5]
	s_lshl_b32 s20, s23, 14
	s_add_u32 s18, s20, s18
	v_and_b32_e32 v0, 15, v32
	s_addc_u32 s19, 0, s19
	v_bfe_u32 v2, v32, 4, 2
	v_and_b32_e32 v3, 7, v3
	v_or_b32_e32 v4, s18, v0
	v_mov_b32_e32 v5, s19
	v_lshl_or_b32 v2, s4, 2, v2
	v_and_b32_e32 v16, 0x180, v18
	v_lshlrev_b32_e32 v3, 4, v3
	v_lshlrev_b64 v[4:5], 8, v[4:5]
	v_or3_b32 v14, v14, v16, v3
	v_or3_b32 v12, v12, v16, v3
	v_or3_b32 v10, v10, v16, v3
	v_or3_b32 v8, v8, v16, v3
	v_or_b32_e32 v4, s26, v4
	v_ashrrev_i32_e32 v3, 31, v2
	v_lshlrev_b32_e32 v72, 2, v2
	v_lshl_add_u64 v[2:3], v[2:3], 2, v[4:5]
	v_readlane_b32 s28, v254, 49
	v_lshl_add_u64 v[60:61], s[92:93], 0, v[2:3]
	v_mov_b32_e32 v2, v1
	v_mov_b32_e32 v3, v1
	v_lshlrev_b32_e32 v71, 4, v0
	v_cmp_gt_u32_e64 s[4:5], 8, v0
	s_movk_i32 s12, 0x180
	v_readlane_b32 s29, v254, 50
	v_mov_b32_e32 v0, v1
	v_mov_b64_e32 v[4:5], v[2:3]
	s_mov_b32 s22, 0
	v_cmp_gt_i32_e64 s[12:13], s12, v32
	v_and_b32_e32 v82, 48, v18
	v_lshl_add_u64 v[48:49], s[28:29], 0, v[14:15]
	v_lshl_add_u64 v[50:51], s[28:29], 0, v[12:13]
	v_lshl_add_u64 v[52:53], s[28:29], 0, v[10:11]
	v_lshl_add_u64 v[54:55], s[28:29], 0, v[8:9]
	v_mov_b64_e32 v[2:3], v[0:1]
	s_waitcnt lgkmcnt(0)
	s_barrier
	s_and_b64 vcc, exec, s[16:17]
	s_cbranch_vccz .Lscan_ldprime
	s_setprio 3
	v_lshlrev_b32_e32 v96, 5, v72
	v_add_u32_e32 v96, 0x1f800, v96
	ds_read_b128 v[116:119], v96
	ds_read_b128 v[132:135], v71 offset:768
	ds_read_b128 v[120:123], v71
	ds_read_b128 v[128:131], v71 offset:512
	ds_read_b128 v[124:127], v71 offset:256
	ds_read_b128 v[136:139], v71 offset:1024
	ds_read_b128 v[156:159], v71 offset:2112
	ds_read_b128 v[144:147], v71 offset:1344
	ds_read_b128 v[152:155], v71 offset:1856
	ds_read_b128 v[148:151], v71 offset:1600
	ds_read_b128 v[160:163], v71 offset:2368
	s_mov_b32 s18, 0
	s_mov_b32 s19, 0xa800
	v_lshl_add_u64 v[62:63], v[60:61], 0, s[14:15]
	s_mov_b64 s[20:21], 0x16100000
	v_lshl_add_u64 v[88:89], v[62:63], 0, s[20:21]
	s_mov_b64 s[20:21], 0x16101000
	v_lshl_add_u64 v[90:91], v[62:63], 0, s[20:21]
	s_branch .Lscan_top

; #define LAS __attribute__((address_space(3)))
; __device__ __forceinline__ float row16_sum(float v) { v += dpp_f<0xB1>(v); v += dpp_f<0x4E>(v); v += dpp_f<0x141>(v); v += dpp_f<0x140>(v); return v; }
; __device__ __forceinline__ void rwkv_scan_unit(LAS unsigned char* lds, const float* Wd, const float* V, const bf16_t* RKKB, float* Yraw, int p, int rg, int tid) {
;     ...
;     for (int c = 0; c < NCH; ++c) {
;         if (wave >= 4) { if (c + 2 < NCH) scan_load_chunk(lds + ((c + 2) % 3) * SCAN_SLOT_B, Wd, V, RKKB, p, rg, (c + 2) * SCAN_CH, tid - 256); }
;         else {
;             LAS const unsigned char* sl = lds + (c % 3) * SCAN_SLOT_B + kq * 16;
;             LAS const unsigned char* vl = lds + (c % 3) * SCAN_SLOT_B + 1280 + rl * 4;
;             float* yo = Yraw + ((size_t)p * SEQ + c * SCAN_CH + kq) * 64 + rg * 16 + rl;
;             f32x4 w = *(LAS const f32x4*)(sl), b = *(LAS const f32x4*)(sl + 256), k = *(LAS const f32x4*)(sl + 512), kk = *(LAS const f32x4*)(sl + 768), r = *(LAS const f32x4*)(sl + 1024);
;             float v = *(LAS const float*)(vl); float yp[16];
; #pragma unroll
;             for (int st = 0; st < SCAN_CH; ++st) {
;                 f32x4 wn = w, bn = b, kn = k, kkn = kk, rn = r; float vn = v;
;                 if (st + 1 < SCAN_CH) { const int o = (st + 1) * SCAN_STEP_B;
;                     wn = *(LAS const f32x4*)(sl + o); bn = *(LAS const f32x4*)(sl + o + 256); kn = *(LAS const f32x4*)(sl + o + 512); kkn = *(LAS const f32x4*)(sl + o + 768); rn = *(LAS const f32x4*)(sl + o + 1024);
;                     vn = *(LAS const float*)(vl + o); }
;                 float sa = (S[0] * kk[0] + S[1] * kk[1]) + (S[2] * kk[2] + S[3] * kk[3]);
;                 const f32x4 kvt = k * v;
;                 sa = -row16_sum(sa);
;                 S = S * w + (b * sa + kvt);
;                 yp[st & 15] = (S[0] * r[0] + S[1] * r[1]) + (S[2] * r[2] + S[3] * r[3]);
;                 if ((st & 15) == 15) yo[(size_t)(st - 15) * 64] = tr16_sum(yp, kq);
;                 w = wn; b = bn; k = kn; kk = kkn; r = rn; v = vn;
;             }
.Lscan_top:
	v_add_u32_e32 v84, s18, v71
	v_add_u32_e32 v86, s19, v71
	s_lshr_b32 s20, s18, 15
	s_lshl_b32 s20, s20, 11
	s_add_i32 s20, s20, 0x1f800
	v_lshl_add_u32 v96, v72, 5, s20
	s_lshr_b32 s21, s19, 15
	s_lshl_b32 s21, s21, 11
	s_add_i32 s21, s21, 0x1f800
	v_lshl_add_u32 v97, v72, 5, s21
	s_waitcnt lgkmcnt(5)
	v_pk_mul_f32 v[10:11], v[2:3], v[132:133]
	v_pk_fma_f32 v[10:11], v[4:5], v[134:135], v[10:11]
	v_pk_mul_f32 v[6:7], v[128:129], v[116:117] op_sel_hi:[1,0]
	v_add_f32_e32 v12, v10, v11
	v_pk_mul_f32 v[8:9], v[130:131], v[116:117] op_sel_hi:[1,0]
	v_pk_fma_f32 v[6:7], v[2:3], v[120:121], v[6:7]
	v_add_f32_dpp v12, v12, v12 quad_perm:[1,0,3,2] row_mask:0xf bank_mask:0xf bound_ctrl:1
	v_pk_fma_f32 v[8:9], v[4:5], v[122:123], v[8:9]
	ds_read_b128 v[180:183], v84 offset:3456
	v_add_f32_dpp v12, v12, v12 quad_perm:[2,3,0,1] row_mask:0xf bank_mask:0xf bound_ctrl:1
	ds_read_b128 v[168:171], v84 offset:2688
	ds_read_b128 v[176:179], v84 offset:3200
	v_add_f32_dpp v12, v12, v12 row_half_mirror row_mask:0xf bank_mask:0xf bound_ctrl:1
	ds_read_b128 v[172:175], v84 offset:2944
	ds_read_b128 v[184:187], v84 offset:3712
	v_add_f32_dpp v12, v12, v12 row_mirror row_mask:0xf bank_mask:0xf bound_ctrl:1
	v_pk_fma_f32 v[2:3], v[124:125], v[12:13], v[6:7] op_sel_hi:[1,0,1] neg_lo:[0,1,0] neg_hi:[0,1,0]
	v_pk_fma_f32 v[4:5], v[126:127], v[12:13], v[8:9] op_sel_hi:[1,0,1] neg_lo:[0,1,0] neg_hi:[0,1,0]
	s_waitcnt lgkmcnt(5)
	v_pk_mul_f32 v[10:11], v[2:3], v[156:157]
	v_pk_fma_f32 v[10:11], v[4:5], v[158:159], v[10:11]
	v_pk_mul_f32 v[14:15], v[2:3], v[136:137]
	v_add_f32_e32 v12, v10, v11
	v_pk_fma_f32 v[14:15], v[4:5], v[138:139], v[14:15]
	v_add_f32_e32 v100, v14, v15
	v_add_f32_dpp v12, v12, v12 quad_perm:[1,0,3,2] row_mask:0xf bank_mask:0xf bound_ctrl:1
	v_pk_mul_f32 v[6:7], v[152:153], v[116:117] op_sel:[0,1] op_sel_hi:[1,1]
	v_pk_mul_f32 v[8:9], v[154:155], v[116:117] op_sel:[0,1] op_sel_hi:[1,1]
	v_add_f32_dpp v12, v12, v12 quad_perm:[2,3,0,1] row_mask:0xf bank_mask:0xf bound_ctrl:1
	v_pk_fma_f32 v[6:7], v[2:3], v[144:145], v[6:7]
	v_pk_fma_f32 v[8:9], v[4:5], v[146:147], v[8:9]
	v_add_f32_dpp v12, v12, v12 row_half_mirror row_mask:0xf bank_mask:0xf bound_ctrl:1
	ds_read_b128 v[34:37], v84 offset:4800
	ds_read_b128 v[22:25], v84 offset:4032
	v_add_f32_dpp v12, v12, v12 row_mirror row_mask:0xf bank_mask:0xf bound_ctrl:1
	ds_read_b128 v[30:33], v84 offset:4544
	ds_read_b128 v[26:29], v84 offset:4288
	ds_read_b128 v[38:41], v84 offset:5056
	v_pk_fma_f32 v[2:3], v[148:149], v[12:13], v[6:7] op_sel_hi:[1,0,1] neg_lo:[0,1,0] neg_hi:[0,1,0]
	v_pk_fma_f32 v[4:5], v[150:151], v[12:13], v[8:9] op_sel_hi:[1,0,1] neg_lo:[0,1,0] neg_hi:[0,1,0]
	s_waitcnt lgkmcnt(5)
	v_pk_mul_f32 v[10:11], v[2:3], v[180:181]
	v_pk_fma_f32 v[10:11], v[4:5], v[182:183], v[10:11]
	v_pk_mul_f32 v[14:15], v[2:3], v[160:161]
	v_add_f32_e32 v12, v10, v11
	v_pk_fma_f32 v[14:15], v[4:5], v[162:163], v[14:15]
	v_add_f32_e32 v101, v14, v15
	v_add_f32_dpp v12, v12, v12 quad_perm:[1,0,3,2] row_mask:0xf bank_mask:0xf bound_ctrl:1
	v_pk_mul_f32 v[6:7], v[176:177], v[118:119] op_sel_hi:[1,0]
	v_pk_mul_f32 v[8:9], v[178:179], v[118:119] op_sel_hi:[1,0]
	v_add_f32_dpp v12, v12, v12 quad_perm:[2,3,0,1] row_mask:0xf bank_mask:0xf bound_ctrl:1
	v_pk_fma_f32 v[6:7], v[2:3], v[168:169], v[6:7]
	v_pk_fma_f32 v[8:9], v[4:5], v[170:171], v[8:9]
	v_add_f32_dpp v12, v12, v12 row_half_mirror row_mask:0xf bank_mask:0xf bound_ctrl:1
	ds_read_b128 v[132:135], v84 offset:6144
	ds_read_b128 v[120:123], v84 offset:5376
	v_add_f32_dpp v12, v12, v12 row_mirror row_mask:0xf bank_mask:0xf bound_ctrl:1
	ds_read_b128 v[128:131], v84 offset:5888
	ds_read_b128 v[92:95], v96 offset:16
	ds_read_b128 v[124:127], v84 offset:5632
	ds_read_b128 v[136:139], v84 offset:6400
	v_pk_fma_f32 v[2:3], v[172:173], v[12:13], v[6:7] op_sel_hi:[1,0,1] neg_lo:[0,1,0] neg_hi:[0,1,0]
	v_pk_fma_f32 v[4:5], v[174:175], v[12:13], v[8:9] op_sel_hi:[1,0,1] neg_lo:[0,1,0] neg_hi:[0,1,0]
	s_waitcnt lgkmcnt(6)
	v_pk_mul_f32 v[10:11], v[2:3], v[34:35]
	v_pk_fma_f32 v[10:11], v[4:5], v[36:37], v[10:11]
	v_pk_mul_f32 v[14:15], v[2:3], v[184:185]
	v_add_f32_e32 v12, v10, v11
	v_pk_fma_f32 v[14:15], v[4:5], v[186:187], v[14:15]
	v_add_f32_e32 v102, v14, v15
	v_add_f32_dpp v12, v12, v12 quad_perm:[1,0,3,2] row_mask:0xf bank_mask:0xf bound_ctrl:1
	v_pk_mul_f32 v[6:7], v[30:31], v[118:119] op_sel:[0,1] op_sel_hi:[1,1]
	v_pk_mul_f32 v[8:9], v[32:33], v[118:119] op_sel:[0,1] op_sel_hi:[1,1]
	v_add_f32_dpp v12, v12, v12 quad_perm:[2,3,0,1] row_mask:0xf bank_mask:0xf bound_ctrl:1
	v_pk_fma_f32 v[6:7], v[2:3], v[22:23], v[6:7]
	v_pk_fma_f32 v[8:9], v[4:5], v[24:25], v[8:9]
	v_add_f32_dpp v12, v12, v12 row_half_mirror row_mask:0xf bank_mask:0xf bound_ctrl:1
	ds_read_b128 v[156:159], v84 offset:7488
	ds_read_b128 v[144:147], v84 offset:6720
	v_add_f32_dpp v12, v12, v12 row_mirror row_mask:0xf bank_mask:0xf bound_ctrl:1
	ds_read_b128 v[152:155], v84 offset:7232
	ds_read_b128 v[148:151], v84 offset:6976
	ds_read_b128 v[160:163], v84 offset:7744
	v_pk_fma_f32 v[2:3], v[26:27], v[12:13], v[6:7] op_sel_hi:[1,0,1] neg_lo:[0,1,0] neg_hi:[0,1,0]
	v_pk_fma_f32 v[4:5], v[28:29], v[12:13], v[8:9] op_sel_hi:[1,0,1] neg_lo:[0,1,0] neg_hi:[0,1,0]
	s_waitcnt lgkmcnt(5)
; #define LAS __attribute__((address_space(3)))
; __device__ __forceinline__ float row16_sum(float v) { v += dpp_f<0xB1>(v); v += dpp_f<0x4E>(v); v += dpp_f<0x141>(v); v += dpp_f<0x140>(v); return v; }
; __device__ __forceinline__ void rwkv_scan_unit(LAS unsigned char* lds, const float* Wd, const float* V, const bf16_t* RKKB, float* Yraw, int p, int rg, int tid) {
;     ...
;             for (int st = 0; st < SCAN_CH; ++st) {
;                 f32x4 wn = w, bn = b, kn = k, kkn = kk, rn = r; float vn = v;
;                 if (st + 1 < SCAN_CH) { const int o = (st + 1) * SCAN_STEP_B;
;                     wn = *(LAS const f32x4*)(sl + o); bn = *(LAS const f32x4*)(sl + o + 256); kn = *(LAS const f32x4*)(sl + o + 512); kkn = *(LAS const f32x4*)(sl + o + 768); rn = *(LAS const f32x4*)(sl + o + 1024);
;                     vn = *(LAS const float*)(vl + o); }
;                 float sa = (S[0] * kk[0] + S[1] * kk[1]) + (S[2] * kk[2] + S[3] * kk[3]);
;                 const f32x4 kvt = k * v;
;                 sa = -row16_sum(sa);
;                 S = S * w + (b * sa + kvt);
;                 yp[st & 15] = (S[0] * r[0] + S[1] * r[1]) + (S[2] * r[2] + S[3] * r[3]);
;                 if ((st & 15) == 15) yo[(size_t)(st - 15) * 64] = tr16_sum(yp, kq);
;                 w = wn; b = bn; k = kn; kk = kkn; r = rn; v = vn;
	v_pk_mul_f32 v[10:11], v[2:3], v[132:133]
	v_pk_fma_f32 v[10:11], v[4:5], v[134:135], v[10:11]
	v_pk_mul_f32 v[14:15], v[2:3], v[38:39]
	v_add_f32_e32 v12, v10, v11
	v_pk_fma_f32 v[14:15], v[4:5], v[40:41], v[14:15]
	v_add_f32_e32 v103, v14, v15
	v_add_f32_dpp v12, v12, v12 quad_perm:[1,0,3,2] row_mask:0xf bank_mask:0xf bound_ctrl:1
	v_pk_mul_f32 v[6:7], v[128:129], v[92:93] op_sel_hi:[1,0]
	v_pk_mul_f32 v[8:9], v[130:131], v[92:93] op_sel_hi:[1,0]
	v_add_f32_dpp v12, v12, v12 quad_perm:[2,3,0,1] row_mask:0xf bank_mask:0xf bound_ctrl:1
	v_pk_fma_f32 v[6:7], v[2:3], v[120:121], v[6:7]
	v_pk_fma_f32 v[8:9], v[4:5], v[122:123], v[8:9]
	v_add_f32_dpp v12, v12, v12 row_half_mirror row_mask:0xf bank_mask:0xf bound_ctrl:1
	ds_read_b128 v[180:183], v84 offset:8832
	ds_read_b128 v[168:171], v84 offset:8064
	v_add_f32_dpp v12, v12, v12 row_mirror row_mask:0xf bank_mask:0xf bound_ctrl:1
	ds_read_b128 v[176:179], v84 offset:8576
	ds_read_b128 v[172:175], v84 offset:8320
	ds_read_b128 v[184:187], v84 offset:9088
	v_pk_fma_f32 v[2:3], v[124:125], v[12:13], v[6:7] op_sel_hi:[1,0,1] neg_lo:[0,1,0] neg_hi:[0,1,0]
	v_pk_fma_f32 v[4:5], v[126:127], v[12:13], v[8:9] op_sel_hi:[1,0,1] neg_lo:[0,1,0] neg_hi:[0,1,0]
	s_waitcnt lgkmcnt(5)
	v_pk_mul_f32 v[10:11], v[2:3], v[156:157]
	v_pk_fma_f32 v[10:11], v[4:5], v[158:159], v[10:11]
	v_pk_mul_f32 v[14:15], v[2:3], v[136:137]
	v_add_f32_e32 v12, v10, v11
	v_pk_fma_f32 v[14:15], v[4:5], v[138:139], v[14:15]
	v_add_f32_e32 v104, v14, v15
	v_add_f32_dpp v12, v12, v12 quad_perm:[1,0,3,2] row_mask:0xf bank_mask:0xf bound_ctrl:1
	v_pk_mul_f32 v[6:7], v[152:153], v[92:93] op_sel:[0,1] op_sel_hi:[1,1]
	v_pk_mul_f32 v[8:9], v[154:155], v[92:93] op_sel:[0,1] op_sel_hi:[1,1]
	v_add_f32_dpp v12, v12, v12 quad_perm:[2,3,0,1] row_mask:0xf bank_mask:0xf bound_ctrl:1
	v_pk_fma_f32 v[6:7], v[2:3], v[144:145], v[6:7]
	v_pk_fma_f32 v[8:9], v[4:5], v[146:147], v[8:9]
	v_add_f32_dpp v12, v12, v12 row_half_mirror row_mask:0xf bank_mask:0xf bound_ctrl:1
	ds_read_b128 v[34:37], v84 offset:10176
	ds_read_b128 v[22:25], v84 offset:9408
	v_add_f32_dpp v12, v12, v12 row_mirror row_mask:0xf bank_mask:0xf bound_ctrl:1
	ds_read_b128 v[30:33], v84 offset:9920
	ds_read_b128 v[26:29], v84 offset:9664
	ds_read_b128 v[38:41], v84 offset:10432
	v_pk_fma_f32 v[2:3], v[148:149], v[12:13], v[6:7] op_sel_hi:[1,0,1] neg_lo:[0,1,0] neg_hi:[0,1,0]
	v_pk_fma_f32 v[4:5], v[150:151], v[12:13], v[8:9] op_sel_hi:[1,0,1] neg_lo:[0,1,0] neg_hi:[0,1,0]
	s_waitcnt lgkmcnt(5)
	v_pk_mul_f32 v[10:11], v[2:3], v[180:181]
	v_pk_fma_f32 v[10:11], v[4:5], v[182:183], v[10:11]
	v_pk_mul_f32 v[14:15], v[2:3], v[160:161]
	v_add_f32_e32 v12, v10, v11
	v_pk_fma_f32 v[14:15], v[4:5], v[162:163], v[14:15]
	v_add_f32_e32 v105, v14, v15
	v_add_f32_dpp v12, v12, v12 quad_perm:[1,0,3,2] row_mask:0xf bank_mask:0xf bound_ctrl:1
	v_pk_mul_f32 v[6:7], v[176:177], v[94:95] op_sel_hi:[1,0]
	v_pk_mul_f32 v[8:9], v[178:179], v[94:95] op_sel_hi:[1,0]
	v_add_f32_dpp v12, v12, v12 quad_perm:[2,3,0,1] row_mask:0xf bank_mask:0xf bound_ctrl:1
	v_pk_fma_f32 v[6:7], v[2:3], v[168:169], v[6:7]
	v_pk_fma_f32 v[8:9], v[4:5], v[170:171], v[8:9]
	v_add_f32_dpp v12, v12, v12 row_half_mirror row_mask:0xf bank_mask:0xf bound_ctrl:1
	ds_read_b128 v[132:135], v84 offset:11520
	ds_read_b128 v[120:123], v84 offset:10752
	v_add_f32_dpp v12, v12, v12 row_mirror row_mask:0xf bank_mask:0xf bound_ctrl:1
	ds_read_b128 v[128:131], v84 offset:11264
	ds_read_b128 v[116:119], v96 offset:32
	ds_read_b128 v[124:127], v84 offset:11008
	ds_read_b128 v[136:139], v84 offset:11776
	v_pk_fma_f32 v[2:3], v[172:173], v[12:13], v[6:7] op_sel_hi:[1,0,1] neg_lo:[0,1,0] neg_hi:[0,1,0]
	v_pk_fma_f32 v[4:5], v[174:175], v[12:13], v[8:9] op_sel_hi:[1,0,1] neg_lo:[0,1,0] neg_hi:[0,1,0]
	s_waitcnt lgkmcnt(6)
	v_pk_mul_f32 v[10:11], v[2:3], v[34:35]
	v_pk_fma_f32 v[10:11], v[4:5], v[36:37], v[10:11]
	v_pk_mul_f32 v[14:15], v[2:3], v[184:185]
	v_add_f32_e32 v12, v10, v11
	v_pk_fma_f32 v[14:15], v[4:5], v[186:187], v[14:15]
	v_add_f32_e32 v106, v14, v15
	v_add_f32_dpp v12, v12, v12 quad_perm:[1,0,3,2] row_mask:0xf bank_mask:0xf bound_ctrl:1
	v_pk_mul_f32 v[6:7], v[30:31], v[94:95] op_sel:[0,1] op_sel_hi:[1,1]
	v_pk_mul_f32 v[8:9], v[32:33], v[94:95] op_sel:[0,1] op_sel_hi:[1,1]
	v_add_f32_dpp v12, v12, v12 quad_perm:[2,3,0,1] row_mask:0xf bank_mask:0xf bound_ctrl:1
	v_pk_fma_f32 v[6:7], v[2:3], v[22:23], v[6:7]
	v_pk_fma_f32 v[8:9], v[4:5], v[24:25], v[8:9]
	v_add_f32_dpp v12, v12, v12 row_half_mirror row_mask:0xf bank_mask:0xf bound_ctrl:1
	ds_read_b128 v[156:159], v84 offset:12864
	ds_read_b128 v[144:147], v84 offset:12096
	v_add_f32_dpp v12, v12, v12 row_mirror row_mask:0xf bank_mask:0xf bound_ctrl:1
	ds_read_b128 v[152:155], v84 offset:12608
	ds_read_b128 v[148:151], v84 offset:12352
	ds_read_b128 v[160:163], v84 offset:13120
	v_pk_fma_f32 v[2:3], v[26:27], v[12:13], v[6:7] op_sel_hi:[1,0,1] neg_lo:[0,1,0] neg_hi:[0,1,0]
	v_pk_fma_f32 v[4:5], v[28:29], v[12:13], v[8:9] op_sel_hi:[1,0,1] neg_lo:[0,1,0] neg_hi:[0,1,0]
	s_waitcnt lgkmcnt(5)
; #define LAS __attribute__((address_space(3)))
; __device__ __forceinline__ float row16_sum(float v) { v += dpp_f<0xB1>(v); v += dpp_f<0x4E>(v); v += dpp_f<0x141>(v); v += dpp_f<0x140>(v); return v; }
; __device__ __forceinline__ void rwkv_scan_unit(LAS unsigned char* lds, const float* Wd, const float* V, const bf16_t* RKKB, float* Yraw, int p, int rg, int tid) {
;     ...
;             for (int st = 0; st < SCAN_CH; ++st) {
;                 f32x4 wn = w, bn = b, kn = k, kkn = kk, rn = r; float vn = v;
;                 if (st + 1 < SCAN_CH) { const int o = (st + 1) * SCAN_STEP_B;
;                     wn = *(LAS const f32x4*)(sl + o); bn = *(LAS const f32x4*)(sl + o + 256); kn = *(LAS const f32x4*)(sl + o + 512); kkn = *(LAS const f32x4*)(sl + o + 768); rn = *(LAS const f32x4*)(sl + o + 1024);
;                     vn = *(LAS const float*)(vl + o); }
;                 float sa = (S[0] * kk[0] + S[1] * kk[1]) + (S[2] * kk[2] + S[3] * kk[3]);
;                 const f32x4 kvt = k * v;
;                 sa = -row16_sum(sa);
;                 S = S * w + (b * sa + kvt);
;                 yp[st & 15] = (S[0] * r[0] + S[1] * r[1]) + (S[2] * r[2] + S[3] * r[3]);
;                 if ((st & 15) == 15) yo[(size_t)(st - 15) * 64] = tr16_sum(yp, kq);
;                 w = wn; b = bn; k = kn; kk = kkn; r = rn; v = vn;
	v_pk_mul_f32 v[10:11], v[2:3], v[132:133]
	v_pk_fma_f32 v[10:11], v[4:5], v[134:135], v[10:11]
	v_pk_mul_f32 v[14:15], v[2:3], v[38:39]
	v_add_f32_e32 v12, v10, v11
	v_pk_fma_f32 v[14:15], v[4:5], v[40:41], v[14:15]
	v_add_f32_e32 v107, v14, v15
	v_add_f32_dpp v12, v12, v12 quad_perm:[1,0,3,2] row_mask:0xf bank_mask:0xf bound_ctrl:1
	v_pk_mul_f32 v[6:7], v[128:129], v[116:117] op_sel_hi:[1,0]
	v_pk_mul_f32 v[8:9], v[130:131], v[116:117] op_sel_hi:[1,0]
	v_add_f32_dpp v12, v12, v12 quad_perm:[2,3,0,1] row_mask:0xf bank_mask:0xf bound_ctrl:1
	v_pk_fma_f32 v[6:7], v[2:3], v[120:121], v[6:7]
	v_pk_fma_f32 v[8:9], v[4:5], v[122:123], v[8:9]
	v_add_f32_dpp v12, v12, v12 row_half_mirror row_mask:0xf bank_mask:0xf bound_ctrl:1
	ds_read_b128 v[180:183], v84 offset:14208
	ds_read_b128 v[168:171], v84 offset:13440
	v_add_f32_dpp v12, v12, v12 row_mirror row_mask:0xf bank_mask:0xf bound_ctrl:1
	ds_read_b128 v[176:179], v84 offset:13952
	ds_read_b128 v[172:175], v84 offset:13696
	ds_read_b128 v[184:187], v84 offset:14464
	v_pk_fma_f32 v[2:3], v[124:125], v[12:13], v[6:7] op_sel_hi:[1,0,1] neg_lo:[0,1,0] neg_hi:[0,1,0]
	v_pk_fma_f32 v[4:5], v[126:127], v[12:13], v[8:9] op_sel_hi:[1,0,1] neg_lo:[0,1,0] neg_hi:[0,1,0]
	s_waitcnt lgkmcnt(5)
	v_pk_mul_f32 v[10:11], v[2:3], v[156:157]
	v_pk_fma_f32 v[10:11], v[4:5], v[158:159], v[10:11]
	v_pk_mul_f32 v[14:15], v[2:3], v[136:137]
	v_add_f32_e32 v12, v10, v11
	v_pk_fma_f32 v[14:15], v[4:5], v[138:139], v[14:15]
	v_add_f32_e32 v44, v14, v15
	v_add_f32_dpp v12, v12, v12 quad_perm:[1,0,3,2] row_mask:0xf bank_mask:0xf bound_ctrl:1
	v_add_f32_dpp v100, v100, v100 row_mirror row_mask:0xf bank_mask:0x3 bound_ctrl:1
	v_add_f32_dpp v100, v44, v44 row_mirror row_mask:0xf bank_mask:0xc bound_ctrl:1
	v_add_f32_dpp v12, v12, v12 quad_perm:[2,3,0,1] row_mask:0xf bank_mask:0xf bound_ctrl:1
	v_pk_mul_f32 v[6:7], v[152:153], v[116:117] op_sel:[0,1] op_sel_hi:[1,1]
	v_pk_mul_f32 v[8:9], v[154:155], v[116:117] op_sel:[0,1] op_sel_hi:[1,1]
	v_add_f32_dpp v12, v12, v12 row_half_mirror row_mask:0xf bank_mask:0xf bound_ctrl:1
	v_pk_fma_f32 v[6:7], v[2:3], v[144:145], v[6:7]
	v_pk_fma_f32 v[8:9], v[4:5], v[146:147], v[8:9]
	v_add_f32_dpp v12, v12, v12 row_mirror row_mask:0xf bank_mask:0xf bound_ctrl:1
	ds_read_b128 v[34:37], v84 offset:15552
	ds_read_b128 v[22:25], v84 offset:14784
	ds_read_b128 v[30:33], v84 offset:15296
	ds_read_b128 v[26:29], v84 offset:15040
	ds_read_b128 v[38:41], v84 offset:15808
	v_pk_fma_f32 v[2:3], v[148:149], v[12:13], v[6:7] op_sel_hi:[1,0,1] neg_lo:[0,1,0] neg_hi:[0,1,0]
	v_pk_fma_f32 v[4:5], v[150:151], v[12:13], v[8:9] op_sel_hi:[1,0,1] neg_lo:[0,1,0] neg_hi:[0,1,0]
	s_waitcnt lgkmcnt(5)
	v_pk_mul_f32 v[10:11], v[2:3], v[180:181]
	v_pk_fma_f32 v[10:11], v[4:5], v[182:183], v[10:11]
	v_pk_mul_f32 v[14:15], v[2:3], v[160:161]
	v_add_f32_e32 v12, v10, v11
	v_pk_fma_f32 v[14:15], v[4:5], v[162:163], v[14:15]
	v_add_f32_e32 v44, v14, v15
	v_add_f32_dpp v12, v12, v12 quad_perm:[1,0,3,2] row_mask:0xf bank_mask:0xf bound_ctrl:1
	v_add_f32_dpp v101, v101, v101 row_mirror row_mask:0xf bank_mask:0x3 bound_ctrl:1
	v_add_f32_dpp v101, v44, v44 row_mirror row_mask:0xf bank_mask:0xc bound_ctrl:1
	v_add_f32_dpp v12, v12, v12 quad_perm:[2,3,0,1] row_mask:0xf bank_mask:0xf bound_ctrl:1
	v_pk_mul_f32 v[6:7], v[176:177], v[118:119] op_sel_hi:[1,0]
	v_pk_mul_f32 v[8:9], v[178:179], v[118:119] op_sel_hi:[1,0]
	v_add_f32_dpp v12, v12, v12 row_half_mirror row_mask:0xf bank_mask:0xf bound_ctrl:1
	v_pk_fma_f32 v[6:7], v[2:3], v[168:169], v[6:7]
	v_pk_fma_f32 v[8:9], v[4:5], v[170:171], v[8:9]
	v_add_f32_dpp v12, v12, v12 row_mirror row_mask:0xf bank_mask:0xf bound_ctrl:1
	ds_read_b128 v[132:135], v84 offset:16896
	ds_read_b128 v[120:123], v84 offset:16128
	ds_read_b128 v[128:131], v84 offset:16640
	ds_read_b128 v[92:95], v96 offset:48
	ds_read_b128 v[124:127], v84 offset:16384
	ds_read_b128 v[136:139], v84 offset:17152
	v_pk_fma_f32 v[2:3], v[172:173], v[12:13], v[6:7] op_sel_hi:[1,0,1] neg_lo:[0,1,0] neg_hi:[0,1,0]
	v_pk_fma_f32 v[4:5], v[174:175], v[12:13], v[8:9] op_sel_hi:[1,0,1] neg_lo:[0,1,0] neg_hi:[0,1,0]
	s_waitcnt lgkmcnt(6)
	v_pk_mul_f32 v[10:11], v[2:3], v[34:35]
	v_pk_fma_f32 v[10:11], v[4:5], v[36:37], v[10:11]
	v_pk_mul_f32 v[14:15], v[2:3], v[184:185]
	v_add_f32_e32 v12, v10, v11
	v_pk_fma_f32 v[14:15], v[4:5], v[186:187], v[14:15]
	v_add_f32_e32 v44, v14, v15
	v_add_f32_dpp v12, v12, v12 quad_perm:[1,0,3,2] row_mask:0xf bank_mask:0xf bound_ctrl:1
	v_add_f32_dpp v102, v102, v102 row_mirror row_mask:0xf bank_mask:0x3 bound_ctrl:1
	v_add_f32_dpp v102, v44, v44 row_mirror row_mask:0xf bank_mask:0xc bound_ctrl:1
	v_add_f32_dpp v12, v12, v12 quad_perm:[2,3,0,1] row_mask:0xf bank_mask:0xf bound_ctrl:1
	v_pk_mul_f32 v[6:7], v[30:31], v[118:119] op_sel:[0,1] op_sel_hi:[1,1]
	v_pk_mul_f32 v[8:9], v[32:33], v[118:119] op_sel:[0,1] op_sel_hi:[1,1]
	v_add_f32_dpp v12, v12, v12 row_half_mirror row_mask:0xf bank_mask:0xf bound_ctrl:1
	v_pk_fma_f32 v[6:7], v[2:3], v[22:23], v[6:7]
	v_pk_fma_f32 v[8:9], v[4:5], v[24:25], v[8:9]
	v_add_f32_dpp v12, v12, v12 row_mirror row_mask:0xf bank_mask:0xf bound_ctrl:1
	ds_read_b128 v[156:159], v84 offset:18240
	ds_read_b128 v[144:147], v84 offset:17472
	ds_read_b128 v[152:155], v84 offset:17984
	ds_read_b128 v[148:151], v84 offset:17728
	ds_read_b128 v[160:163], v84 offset:18496
	v_pk_fma_f32 v[2:3], v[26:27], v[12:13], v[6:7] op_sel_hi:[1,0,1] neg_lo:[0,1,0] neg_hi:[0,1,0]
	v_pk_fma_f32 v[4:5], v[28:29], v[12:13], v[8:9] op_sel_hi:[1,0,1] neg_lo:[0,1,0] neg_hi:[0,1,0]
	s_waitcnt lgkmcnt(5)
; #define LAS __attribute__((address_space(3)))
; __device__ __forceinline__ float row16_sum(float v) { v += dpp_f<0xB1>(v); v += dpp_f<0x4E>(v); v += dpp_f<0x141>(v); v += dpp_f<0x140>(v); return v; }
; __device__ __forceinline__ void rwkv_scan_unit(LAS unsigned char* lds, const float* Wd, const float* V, const bf16_t* RKKB, float* Yraw, int p, int rg, int tid) {
;     ...
;             for (int st = 0; st < SCAN_CH; ++st) {
;                 f32x4 wn = w, bn = b, kn = k, kkn = kk, rn = r; float vn = v;
;                 if (st + 1 < SCAN_CH) { const int o = (st + 1) * SCAN_STEP_B;
;                     wn = *(LAS const f32x4*)(sl + o); bn = *(LAS const f32x4*)(sl + o + 256); kn = *(LAS const f32x4*)(sl + o + 512); kkn = *(LAS const f32x4*)(sl + o + 768); rn = *(LAS const f32x4*)(sl + o + 1024);
;                     vn = *(LAS const float*)(vl + o); }
;                 float sa = (S[0] * kk[0] + S[1] * kk[1]) + (S[2] * kk[2] + S[3] * kk[3]);
;                 const f32x4 kvt = k * v;
;                 sa = -row16_sum(sa);
;                 S = S * w + (b * sa + kvt);
;                 yp[st & 15] = (S[0] * r[0] + S[1] * r[1]) + (S[2] * r[2] + S[3] * r[3]);
;                 if ((st & 15) == 15) yo[(size_t)(st - 15) * 64] = tr16_sum(yp, kq);
;                 w = wn; b = bn; k = kn; kk = kkn; r = rn; v = vn;
	v_pk_mul_f32 v[10:11], v[2:3], v[132:133]
	v_pk_fma_f32 v[10:11], v[4:5], v[134:135], v[10:11]
	v_pk_mul_f32 v[14:15], v[2:3], v[38:39]
	v_add_f32_e32 v12, v10, v11
	v_pk_fma_f32 v[14:15], v[4:5], v[40:41], v[14:15]
	v_add_f32_e32 v44, v14, v15
	v_add_f32_dpp v12, v12, v12 quad_perm:[1,0,3,2] row_mask:0xf bank_mask:0xf bound_ctrl:1
	v_add_f32_dpp v103, v103, v103 row_mirror row_mask:0xf bank_mask:0x3 bound_ctrl:1
	v_add_f32_dpp v103, v44, v44 row_mirror row_mask:0xf bank_mask:0xc bound_ctrl:1
	v_add_f32_dpp v12, v12, v12 quad_perm:[2,3,0,1] row_mask:0xf bank_mask:0xf bound_ctrl:1
	v_pk_mul_f32 v[6:7], v[128:129], v[92:93] op_sel_hi:[1,0]
	v_pk_mul_f32 v[8:9], v[130:131], v[92:93] op_sel_hi:[1,0]
	v_add_f32_dpp v12, v12, v12 row_half_mirror row_mask:0xf bank_mask:0xf bound_ctrl:1
	v_pk_fma_f32 v[6:7], v[2:3], v[120:121], v[6:7]
	v_pk_fma_f32 v[8:9], v[4:5], v[122:123], v[8:9]
	v_add_f32_dpp v12, v12, v12 row_mirror row_mask:0xf bank_mask:0xf bound_ctrl:1
	ds_read_b128 v[180:183], v84 offset:19584
	ds_read_b128 v[168:171], v84 offset:18816
	ds_read_b128 v[176:179], v84 offset:19328
	ds_read_b128 v[172:175], v84 offset:19072
	ds_read_b128 v[184:187], v84 offset:19840
	v_pk_fma_f32 v[2:3], v[124:125], v[12:13], v[6:7] op_sel_hi:[1,0,1] neg_lo:[0,1,0] neg_hi:[0,1,0]
	v_pk_fma_f32 v[4:5], v[126:127], v[12:13], v[8:9] op_sel_hi:[1,0,1] neg_lo:[0,1,0] neg_hi:[0,1,0]
	s_waitcnt lgkmcnt(5)
	v_pk_mul_f32 v[10:11], v[2:3], v[156:157]
	v_pk_fma_f32 v[10:11], v[4:5], v[158:159], v[10:11]
	v_pk_mul_f32 v[14:15], v[2:3], v[136:137]
	v_add_f32_e32 v12, v10, v11
	v_pk_fma_f32 v[14:15], v[4:5], v[138:139], v[14:15]
	v_add_f32_e32 v44, v14, v15
	v_add_f32_dpp v12, v12, v12 quad_perm:[1,0,3,2] row_mask:0xf bank_mask:0xf bound_ctrl:1
	v_add_f32_dpp v104, v104, v104 row_mirror row_mask:0xf bank_mask:0x3 bound_ctrl:1
	v_add_f32_dpp v104, v44, v44 row_mirror row_mask:0xf bank_mask:0xc bound_ctrl:1
	v_add_f32_dpp v12, v12, v12 quad_perm:[2,3,0,1] row_mask:0xf bank_mask:0xf bound_ctrl:1
	v_pk_mul_f32 v[6:7], v[152:153], v[92:93] op_sel:[0,1] op_sel_hi:[1,1]
	v_pk_mul_f32 v[8:9], v[154:155], v[92:93] op_sel:[0,1] op_sel_hi:[1,1]
	v_add_f32_dpp v12, v12, v12 row_half_mirror row_mask:0xf bank_mask:0xf bound_ctrl:1
	v_pk_fma_f32 v[6:7], v[2:3], v[144:145], v[6:7]
	v_pk_fma_f32 v[8:9], v[4:5], v[146:147], v[8:9]
	v_add_f32_dpp v12, v12, v12 row_mirror row_mask:0xf bank_mask:0xf bound_ctrl:1
	ds_read_b128 v[34:37], v84 offset:20928
	ds_read_b128 v[22:25], v84 offset:20160
	ds_read_b128 v[30:33], v84 offset:20672
	ds_read_b128 v[26:29], v84 offset:20416
	ds_read_b128 v[38:41], v84 offset:21184
	v_pk_fma_f32 v[2:3], v[148:149], v[12:13], v[6:7] op_sel_hi:[1,0,1] neg_lo:[0,1,0] neg_hi:[0,1,0]
	v_pk_fma_f32 v[4:5], v[150:151], v[12:13], v[8:9] op_sel_hi:[1,0,1] neg_lo:[0,1,0] neg_hi:[0,1,0]
	s_waitcnt lgkmcnt(5)
	v_pk_mul_f32 v[10:11], v[2:3], v[180:181]
	v_pk_fma_f32 v[10:11], v[4:5], v[182:183], v[10:11]
	v_pk_mul_f32 v[14:15], v[2:3], v[160:161]
	v_add_f32_e32 v12, v10, v11
	v_pk_fma_f32 v[14:15], v[4:5], v[162:163], v[14:15]
	v_add_f32_e32 v44, v14, v15
	v_add_f32_dpp v12, v12, v12 quad_perm:[1,0,3,2] row_mask:0xf bank_mask:0xf bound_ctrl:1
	v_add_f32_dpp v105, v105, v105 row_mirror row_mask:0xf bank_mask:0x3 bound_ctrl:1
	v_add_f32_dpp v105, v44, v44 row_mirror row_mask:0xf bank_mask:0xc bound_ctrl:1
	v_add_f32_dpp v12, v12, v12 quad_perm:[2,3,0,1] row_mask:0xf bank_mask:0xf bound_ctrl:1
	v_pk_mul_f32 v[6:7], v[176:177], v[94:95] op_sel_hi:[1,0]
	v_pk_mul_f32 v[8:9], v[178:179], v[94:95] op_sel_hi:[1,0]
	v_add_f32_dpp v12, v12, v12 row_half_mirror row_mask:0xf bank_mask:0xf bound_ctrl:1
	v_pk_fma_f32 v[6:7], v[2:3], v[168:169], v[6:7]
	v_pk_fma_f32 v[8:9], v[4:5], v[170:171], v[8:9]
	v_add_f32_dpp v12, v12, v12 row_mirror row_mask:0xf bank_mask:0xf bound_ctrl:1
	ds_read_b128 v[132:135], v84 offset:22272
	ds_read_b128 v[120:123], v84 offset:21504
	ds_read_b128 v[128:131], v84 offset:22016
	ds_read_b128 v[116:119], v96 offset:64
	ds_read_b128 v[124:127], v84 offset:21760
	ds_read_b128 v[136:139], v84 offset:22528
	v_pk_fma_f32 v[2:3], v[172:173], v[12:13], v[6:7] op_sel_hi:[1,0,1] neg_lo:[0,1,0] neg_hi:[0,1,0]
	v_pk_fma_f32 v[4:5], v[174:175], v[12:13], v[8:9] op_sel_hi:[1,0,1] neg_lo:[0,1,0] neg_hi:[0,1,0]
	s_waitcnt lgkmcnt(6)
	v_pk_mul_f32 v[10:11], v[2:3], v[34:35]
	v_pk_fma_f32 v[10:11], v[4:5], v[36:37], v[10:11]
	v_pk_mul_f32 v[14:15], v[2:3], v[184:185]
	v_add_f32_e32 v12, v10, v11
	v_pk_fma_f32 v[14:15], v[4:5], v[186:187], v[14:15]
	v_add_f32_e32 v44, v14, v15
	v_add_f32_dpp v12, v12, v12 quad_perm:[1,0,3,2] row_mask:0xf bank_mask:0xf bound_ctrl:1
	v_add_f32_dpp v106, v106, v106 row_mirror row_mask:0xf bank_mask:0x3 bound_ctrl:1
	v_add_f32_dpp v106, v44, v44 row_mirror row_mask:0xf bank_mask:0xc bound_ctrl:1
	v_add_f32_dpp v12, v12, v12 quad_perm:[2,3,0,1] row_mask:0xf bank_mask:0xf bound_ctrl:1
	v_pk_mul_f32 v[6:7], v[30:31], v[94:95] op_sel:[0,1] op_sel_hi:[1,1]
	v_pk_mul_f32 v[8:9], v[32:33], v[94:95] op_sel:[0,1] op_sel_hi:[1,1]
	v_add_f32_dpp v12, v12, v12 row_half_mirror row_mask:0xf bank_mask:0xf bound_ctrl:1
	v_pk_fma_f32 v[6:7], v[2:3], v[22:23], v[6:7]
	v_pk_fma_f32 v[8:9], v[4:5], v[24:25], v[8:9]
	v_add_f32_dpp v12, v12, v12 row_mirror row_mask:0xf bank_mask:0xf bound_ctrl:1
	ds_read_b128 v[156:159], v84 offset:23616
	ds_read_b128 v[144:147], v84 offset:22848
	ds_read_b128 v[152:155], v84 offset:23360
	ds_read_b128 v[148:151], v84 offset:23104
	ds_read_b128 v[160:163], v84 offset:23872
	v_pk_fma_f32 v[2:3], v[26:27], v[12:13], v[6:7] op_sel_hi:[1,0,1] neg_lo:[0,1,0] neg_hi:[0,1,0]
	v_pk_fma_f32 v[4:5], v[28:29], v[12:13], v[8:9] op_sel_hi:[1,0,1] neg_lo:[0,1,0] neg_hi:[0,1,0]
	s_waitcnt lgkmcnt(5)
; #define LAS __attribute__((address_space(3)))
; __device__ __forceinline__ float row16_sum(float v) { v += dpp_f<0xB1>(v); v += dpp_f<0x4E>(v); v += dpp_f<0x141>(v); v += dpp_f<0x140>(v); return v; }
; __device__ __forceinline__ void rwkv_scan_unit(LAS unsigned char* lds, const float* Wd, const float* V, const bf16_t* RKKB, float* Yraw, int p, int rg, int tid) {
;     ...
;             for (int st = 0; st < SCAN_CH; ++st) {
;                 f32x4 wn = w, bn = b, kn = k, kkn = kk, rn = r; float vn = v;
;                 if (st + 1 < SCAN_CH) { const int o = (st + 1) * SCAN_STEP_B;
;                     wn = *(LAS const f32x4*)(sl + o); bn = *(LAS const f32x4*)(sl + o + 256); kn = *(LAS const f32x4*)(sl + o + 512); kkn = *(LAS const f32x4*)(sl + o + 768); rn = *(LAS const f32x4*)(sl + o + 1024);
;                     vn = *(LAS const float*)(vl + o); }
;                 float sa = (S[0] * kk[0] + S[1] * kk[1]) + (S[2] * kk[2] + S[3] * kk[3]);
;                 const f32x4 kvt = k * v;
;                 sa = -row16_sum(sa);
;                 S = S * w + (b * sa + kvt);
;                 yp[st & 15] = (S[0] * r[0] + S[1] * r[1]) + (S[2] * r[2] + S[3] * r[3]);
;                 if ((st & 15) == 15) yo[(size_t)(st - 15) * 64] = tr16_sum(yp, kq);
;                 w = wn; b = bn; k = kn; kk = kkn; r = rn; v = vn;
	v_pk_mul_f32 v[10:11], v[2:3], v[132:133]
	v_pk_fma_f32 v[10:11], v[4:5], v[134:135], v[10:11]
	v_pk_mul_f32 v[14:15], v[2:3], v[38:39]
	v_add_f32_e32 v12, v10, v11
	v_pk_fma_f32 v[14:15], v[4:5], v[40:41], v[14:15]
	v_add_f32_e32 v44, v14, v15
	v_add_f32_dpp v107, v107, v107 row_mirror row_mask:0xf bank_mask:0x3 bound_ctrl:1
	s_nop 0
	v_add_f32_dpp v107, v44, v44 row_mirror row_mask:0xf bank_mask:0xc bound_ctrl:1
	v_add_f32_dpp v12, v12, v12 quad_perm:[1,0,3,2] row_mask:0xf bank_mask:0xf bound_ctrl:1
	v_pk_mul_f32 v[6:7], v[128:129], v[116:117] op_sel_hi:[1,0]
	v_pk_mul_f32 v[8:9], v[130:131], v[116:117] op_sel_hi:[1,0]
	v_pk_fma_f32 v[6:7], v[2:3], v[120:121], v[6:7]
	v_pk_fma_f32 v[8:9], v[4:5], v[122:123], v[8:9]
	v_add_f32_dpp v12, v12, v12 quad_perm:[2,3,0,1] row_mask:0xf bank_mask:0xf bound_ctrl:1
	ds_read_b128 v[180:183], v84 offset:24960
	ds_read_b128 v[168:171], v84 offset:24192
	ds_read_b128 v[176:179], v84 offset:24704
	ds_read_b128 v[172:175], v84 offset:24448
	v_add_f32_dpp v12, v12, v12 row_half_mirror row_mask:0xf bank_mask:0xf bound_ctrl:1
	ds_read_b128 v[184:187], v84 offset:25216
	v_add_f32_dpp v100, v100, v100 row_half_mirror row_mask:0xf bank_mask:0x5 bound_ctrl:1
	v_add_f32_dpp v100, v104, v104 row_half_mirror row_mask:0xf bank_mask:0xa bound_ctrl:1
	v_add_f32_dpp v101, v101, v101 row_half_mirror row_mask:0xf bank_mask:0x5 bound_ctrl:1
	v_add_f32_dpp v12, v12, v12 row_mirror row_mask:0xf bank_mask:0xf bound_ctrl:1
	v_add_f32_dpp v101, v105, v105 row_half_mirror row_mask:0xf bank_mask:0xa bound_ctrl:1
	v_add_f32_dpp v102, v102, v102 row_half_mirror row_mask:0xf bank_mask:0x5 bound_ctrl:1
	v_add_f32_dpp v102, v106, v106 row_half_mirror row_mask:0xf bank_mask:0xa bound_ctrl:1
	v_add_f32_dpp v103, v103, v103 row_half_mirror row_mask:0xf bank_mask:0x5 bound_ctrl:1
	v_add_f32_dpp v103, v107, v107 row_half_mirror row_mask:0xf bank_mask:0xa bound_ctrl:1
	v_cndmask_b32_e64 v16, v102, v100, s[8:9]
	v_pk_fma_f32 v[2:3], v[124:125], v[12:13], v[6:7] op_sel_hi:[1,0,1] neg_lo:[0,1,0] neg_hi:[0,1,0]
	v_pk_fma_f32 v[4:5], v[126:127], v[12:13], v[8:9] op_sel_hi:[1,0,1] neg_lo:[0,1,0] neg_hi:[0,1,0]
	s_waitcnt lgkmcnt(5)
	v_pk_mul_f32 v[10:11], v[2:3], v[156:157]
	v_pk_fma_f32 v[10:11], v[4:5], v[158:159], v[10:11]
	v_pk_mul_f32 v[14:15], v[2:3], v[136:137]
	v_add_f32_e32 v12, v10, v11
	v_pk_fma_f32 v[14:15], v[4:5], v[138:139], v[14:15]
	v_add_f32_e32 v108, v14, v15
	v_pk_mul_f32 v[6:7], v[152:153], v[116:117] op_sel:[0,1] op_sel_hi:[1,1]
	v_pk_mul_f32 v[8:9], v[154:155], v[116:117] op_sel:[0,1] op_sel_hi:[1,1]
	v_add_f32_dpp v12, v12, v12 quad_perm:[1,0,3,2] row_mask:0xf bank_mask:0xf bound_ctrl:1
	v_pk_fma_f32 v[6:7], v[2:3], v[144:145], v[6:7]
	v_pk_fma_f32 v[8:9], v[4:5], v[146:147], v[8:9]
	ds_read_b128 v[34:37], v84 offset:26304
	ds_read_b128 v[22:25], v84 offset:25536
	v_add_f32_dpp v12, v12, v12 quad_perm:[2,3,0,1] row_mask:0xf bank_mask:0xf bound_ctrl:1
	ds_read_b128 v[30:33], v84 offset:26048
	ds_read_b128 v[26:29], v84 offset:25792
	ds_read_b128 v[38:41], v84 offset:26560
	v_cndmask_b32_e64 v17, v100, v102, s[8:9]
	v_add_f32_dpp v12, v12, v12 row_half_mirror row_mask:0xf bank_mask:0xf bound_ctrl:1
	s_nop 0
	v_add_f32_dpp v16, v17, v16 quad_perm:[2,3,0,1] row_mask:0xf bank_mask:0xf bound_ctrl:1
	v_cndmask_b32_e64 v18, v103, v101, s[8:9]
	v_cndmask_b32_e64 v19, v101, v103, s[8:9]
	s_nop 1
	v_add_f32_dpp v18, v19, v18 quad_perm:[2,3,0,1] row_mask:0xf bank_mask:0xf bound_ctrl:1
	v_add_f32_dpp v12, v12, v12 row_mirror row_mask:0xf bank_mask:0xf bound_ctrl:1
	v_cndmask_b32_e64 v17, v18, v16, s[10:11]
	v_cndmask_b32_e64 v19, v16, v18, s[10:11]
	s_nop 1
	v_add_f32_dpp v17, v19, v17 quad_perm:[1,0,3,2] row_mask:0xf bank_mask:0xf bound_ctrl:1
	global_store_dword v[88:89], v17, off
	v_pk_fma_f32 v[2:3], v[148:149], v[12:13], v[6:7] op_sel_hi:[1,0,1] neg_lo:[0,1,0] neg_hi:[0,1,0]
	v_pk_fma_f32 v[4:5], v[150:151], v[12:13], v[8:9] op_sel_hi:[1,0,1] neg_lo:[0,1,0] neg_hi:[0,1,0]
	s_waitcnt lgkmcnt(5)
	v_pk_mul_f32 v[10:11], v[2:3], v[180:181]
	v_pk_fma_f32 v[10:11], v[4:5], v[182:183], v[10:11]
	v_pk_mul_f32 v[14:15], v[2:3], v[160:161]
	v_add_f32_e32 v12, v10, v11
	v_pk_fma_f32 v[14:15], v[4:5], v[162:163], v[14:15]
	v_add_f32_e32 v109, v14, v15
	v_add_f32_dpp v12, v12, v12 quad_perm:[1,0,3,2] row_mask:0xf bank_mask:0xf bound_ctrl:1
	v_pk_mul_f32 v[6:7], v[176:177], v[118:119] op_sel_hi:[1,0]
	v_pk_mul_f32 v[8:9], v[178:179], v[118:119] op_sel_hi:[1,0]
	v_add_f32_dpp v12, v12, v12 quad_perm:[2,3,0,1] row_mask:0xf bank_mask:0xf bound_ctrl:1
	v_pk_fma_f32 v[6:7], v[2:3], v[168:169], v[6:7]
	v_pk_fma_f32 v[8:9], v[4:5], v[170:171], v[8:9]
	v_add_f32_dpp v12, v12, v12 row_half_mirror row_mask:0xf bank_mask:0xf bound_ctrl:1
	ds_read_b128 v[132:135], v84 offset:27648
	ds_read_b128 v[120:123], v84 offset:26880
	v_add_f32_dpp v12, v12, v12 row_mirror row_mask:0xf bank_mask:0xf bound_ctrl:1
	ds_read_b128 v[128:131], v84 offset:27392
	ds_read_b128 v[92:95], v96 offset:80
	ds_read_b128 v[124:127], v84 offset:27136
	ds_read_b128 v[136:139], v84 offset:27904
	v_pk_fma_f32 v[2:3], v[172:173], v[12:13], v[6:7] op_sel_hi:[1,0,1] neg_lo:[0,1,0] neg_hi:[0,1,0]
	v_pk_fma_f32 v[4:5], v[174:175], v[12:13], v[8:9] op_sel_hi:[1,0,1] neg_lo:[0,1,0] neg_hi:[0,1,0]
	s_waitcnt lgkmcnt(6)
; #define LAS __attribute__((address_space(3)))
; __device__ __forceinline__ float row16_sum(float v) { v += dpp_f<0xB1>(v); v += dpp_f<0x4E>(v); v += dpp_f<0x141>(v); v += dpp_f<0x140>(v); return v; }
; __device__ __forceinline__ void rwkv_scan_unit(LAS unsigned char* lds, const float* Wd, const float* V, const bf16_t* RKKB, float* Yraw, int p, int rg, int tid) {
;     ...
;             for (int st = 0; st < SCAN_CH; ++st) {
;                 f32x4 wn = w, bn = b, kn = k, kkn = kk, rn = r; float vn = v;
;                 if (st + 1 < SCAN_CH) { const int o = (st + 1) * SCAN_STEP_B;
;                     wn = *(LAS const f32x4*)(sl + o); bn = *(LAS const f32x4*)(sl + o + 256); kn = *(LAS const f32x4*)(sl + o + 512); kkn = *(LAS const f32x4*)(sl + o + 768); rn = *(LAS const f32x4*)(sl + o + 1024);
;                     vn = *(LAS const float*)(vl + o); }
;                 float sa = (S[0] * kk[0] + S[1] * kk[1]) + (S[2] * kk[2] + S[3] * kk[3]);
;                 const f32x4 kvt = k * v;
;                 sa = -row16_sum(sa);
;                 S = S * w + (b * sa + kvt);
;                 yp[st & 15] = (S[0] * r[0] + S[1] * r[1]) + (S[2] * r[2] + S[3] * r[3]);
;                 if ((st & 15) == 15) yo[(size_t)(st - 15) * 64] = tr16_sum(yp, kq);
;                 w = wn; b = bn; k = kn; kk = kkn; r = rn; v = vn;
	v_pk_mul_f32 v[10:11], v[2:3], v[34:35]
	v_pk_fma_f32 v[10:11], v[4:5], v[36:37], v[10:11]
	v_pk_mul_f32 v[14:15], v[2:3], v[184:185]
	v_add_f32_e32 v12, v10, v11
	v_pk_fma_f32 v[14:15], v[4:5], v[186:187], v[14:15]
	v_add_f32_e32 v110, v14, v15
	v_add_f32_dpp v12, v12, v12 quad_perm:[1,0,3,2] row_mask:0xf bank_mask:0xf bound_ctrl:1
	v_pk_mul_f32 v[6:7], v[30:31], v[118:119] op_sel:[0,1] op_sel_hi:[1,1]
	v_pk_mul_f32 v[8:9], v[32:33], v[118:119] op_sel:[0,1] op_sel_hi:[1,1]
	v_add_f32_dpp v12, v12, v12 quad_perm:[2,3,0,1] row_mask:0xf bank_mask:0xf bound_ctrl:1
	v_pk_fma_f32 v[6:7], v[2:3], v[22:23], v[6:7]
	v_pk_fma_f32 v[8:9], v[4:5], v[24:25], v[8:9]
	v_add_f32_dpp v12, v12, v12 row_half_mirror row_mask:0xf bank_mask:0xf bound_ctrl:1
	ds_read_b128 v[156:159], v84 offset:28992
	ds_read_b128 v[144:147], v84 offset:28224
	v_add_f32_dpp v12, v12, v12 row_mirror row_mask:0xf bank_mask:0xf bound_ctrl:1
	ds_read_b128 v[152:155], v84 offset:28736
	ds_read_b128 v[148:151], v84 offset:28480
	ds_read_b128 v[160:163], v84 offset:29248
	v_pk_fma_f32 v[2:3], v[26:27], v[12:13], v[6:7] op_sel_hi:[1,0,1] neg_lo:[0,1,0] neg_hi:[0,1,0]
	v_pk_fma_f32 v[4:5], v[28:29], v[12:13], v[8:9] op_sel_hi:[1,0,1] neg_lo:[0,1,0] neg_hi:[0,1,0]
	s_waitcnt lgkmcnt(5)
	v_pk_mul_f32 v[10:11], v[2:3], v[132:133]
	v_pk_fma_f32 v[10:11], v[4:5], v[134:135], v[10:11]
	v_pk_mul_f32 v[14:15], v[2:3], v[38:39]
	v_add_f32_e32 v12, v10, v11
	v_pk_fma_f32 v[14:15], v[4:5], v[40:41], v[14:15]
	v_add_f32_e32 v111, v14, v15
	v_add_f32_dpp v12, v12, v12 quad_perm:[1,0,3,2] row_mask:0xf bank_mask:0xf bound_ctrl:1
	v_pk_mul_f32 v[6:7], v[128:129], v[92:93] op_sel_hi:[1,0]
	v_pk_mul_f32 v[8:9], v[130:131], v[92:93] op_sel_hi:[1,0]
	v_add_f32_dpp v12, v12, v12 quad_perm:[2,3,0,1] row_mask:0xf bank_mask:0xf bound_ctrl:1
	v_pk_fma_f32 v[6:7], v[2:3], v[120:121], v[6:7]
	v_pk_fma_f32 v[8:9], v[4:5], v[122:123], v[8:9]
	v_add_f32_dpp v12, v12, v12 row_half_mirror row_mask:0xf bank_mask:0xf bound_ctrl:1
	ds_read_b128 v[180:183], v84 offset:30336
	ds_read_b128 v[168:171], v84 offset:29568
	v_add_f32_dpp v12, v12, v12 row_mirror row_mask:0xf bank_mask:0xf bound_ctrl:1
	ds_read_b128 v[176:179], v84 offset:30080
	ds_read_b128 v[172:175], v84 offset:29824
	ds_read_b128 v[184:187], v84 offset:30592
	v_pk_fma_f32 v[2:3], v[124:125], v[12:13], v[6:7] op_sel_hi:[1,0,1] neg_lo:[0,1,0] neg_hi:[0,1,0]
	v_pk_fma_f32 v[4:5], v[126:127], v[12:13], v[8:9] op_sel_hi:[1,0,1] neg_lo:[0,1,0] neg_hi:[0,1,0]
	s_waitcnt lgkmcnt(5)
	v_pk_mul_f32 v[10:11], v[2:3], v[156:157]
	v_pk_fma_f32 v[10:11], v[4:5], v[158:159], v[10:11]
	v_pk_mul_f32 v[14:15], v[2:3], v[136:137]
	v_add_f32_e32 v12, v10, v11
	v_pk_fma_f32 v[14:15], v[4:5], v[138:139], v[14:15]
	v_add_f32_e32 v112, v14, v15
	v_add_f32_dpp v12, v12, v12 quad_perm:[1,0,3,2] row_mask:0xf bank_mask:0xf bound_ctrl:1
	v_pk_mul_f32 v[6:7], v[152:153], v[92:93] op_sel:[0,1] op_sel_hi:[1,1]
	v_pk_mul_f32 v[8:9], v[154:155], v[92:93] op_sel:[0,1] op_sel_hi:[1,1]
	v_add_f32_dpp v12, v12, v12 quad_perm:[2,3,0,1] row_mask:0xf bank_mask:0xf bound_ctrl:1
	v_pk_fma_f32 v[6:7], v[2:3], v[144:145], v[6:7]
	v_pk_fma_f32 v[8:9], v[4:5], v[146:147], v[8:9]
	v_add_f32_dpp v12, v12, v12 row_half_mirror row_mask:0xf bank_mask:0xf bound_ctrl:1
	ds_read_b128 v[34:37], v84 offset:31680
	ds_read_b128 v[22:25], v84 offset:30912
	v_add_f32_dpp v12, v12, v12 row_mirror row_mask:0xf bank_mask:0xf bound_ctrl:1
	ds_read_b128 v[30:33], v84 offset:31424
	ds_read_b128 v[26:29], v84 offset:31168
	ds_read_b128 v[38:41], v84 offset:31936
	v_pk_fma_f32 v[2:3], v[148:149], v[12:13], v[6:7] op_sel_hi:[1,0,1] neg_lo:[0,1,0] neg_hi:[0,1,0]
	v_pk_fma_f32 v[4:5], v[150:151], v[12:13], v[8:9] op_sel_hi:[1,0,1] neg_lo:[0,1,0] neg_hi:[0,1,0]
	s_waitcnt lgkmcnt(5)
	v_pk_mul_f32 v[10:11], v[2:3], v[180:181]
	v_pk_fma_f32 v[10:11], v[4:5], v[182:183], v[10:11]
	v_pk_mul_f32 v[14:15], v[2:3], v[160:161]
	v_add_f32_e32 v12, v10, v11
	v_pk_fma_f32 v[14:15], v[4:5], v[162:163], v[14:15]
	v_add_f32_e32 v113, v14, v15
	v_add_f32_dpp v12, v12, v12 quad_perm:[1,0,3,2] row_mask:0xf bank_mask:0xf bound_ctrl:1
	v_pk_mul_f32 v[6:7], v[176:177], v[94:95] op_sel_hi:[1,0]
	v_pk_mul_f32 v[8:9], v[178:179], v[94:95] op_sel_hi:[1,0]
	v_add_f32_dpp v12, v12, v12 quad_perm:[2,3,0,1] row_mask:0xf bank_mask:0xf bound_ctrl:1
	v_pk_fma_f32 v[6:7], v[2:3], v[168:169], v[6:7]
	v_pk_fma_f32 v[8:9], v[4:5], v[170:171], v[8:9]
	v_add_f32_dpp v12, v12, v12 row_half_mirror row_mask:0xf bank_mask:0xf bound_ctrl:1
	ds_read_b128 v[132:135], v84 offset:33024
	ds_read_b128 v[120:123], v84 offset:32256
	v_add_f32_dpp v12, v12, v12 row_mirror row_mask:0xf bank_mask:0xf bound_ctrl:1
	ds_read_b128 v[128:131], v84 offset:32768
	ds_read_b128 v[116:119], v96 offset:96
	ds_read_b128 v[124:127], v84 offset:32512
	ds_read_b128 v[136:139], v84 offset:33280
	v_pk_fma_f32 v[2:3], v[172:173], v[12:13], v[6:7] op_sel_hi:[1,0,1] neg_lo:[0,1,0] neg_hi:[0,1,0]
	v_pk_fma_f32 v[4:5], v[174:175], v[12:13], v[8:9] op_sel_hi:[1,0,1] neg_lo:[0,1,0] neg_hi:[0,1,0]
	s_waitcnt lgkmcnt(6)
; #define LAS __attribute__((address_space(3)))
; __device__ __forceinline__ float row16_sum(float v) { v += dpp_f<0xB1>(v); v += dpp_f<0x4E>(v); v += dpp_f<0x141>(v); v += dpp_f<0x140>(v); return v; }
; __device__ __forceinline__ void rwkv_scan_unit(LAS unsigned char* lds, const float* Wd, const float* V, const bf16_t* RKKB, float* Yraw, int p, int rg, int tid) {
;     ...
;             for (int st = 0; st < SCAN_CH; ++st) {
;                 f32x4 wn = w, bn = b, kn = k, kkn = kk, rn = r; float vn = v;
;                 if (st + 1 < SCAN_CH) { const int o = (st + 1) * SCAN_STEP_B;
;                     wn = *(LAS const f32x4*)(sl + o); bn = *(LAS const f32x4*)(sl + o + 256); kn = *(LAS const f32x4*)(sl + o + 512); kkn = *(LAS const f32x4*)(sl + o + 768); rn = *(LAS const f32x4*)(sl + o + 1024);
;                     vn = *(LAS const float*)(vl + o); }
;                 float sa = (S[0] * kk[0] + S[1] * kk[1]) + (S[2] * kk[2] + S[3] * kk[3]);
;                 const f32x4 kvt = k * v;
;                 sa = -row16_sum(sa);
;                 S = S * w + (b * sa + kvt);
;                 yp[st & 15] = (S[0] * r[0] + S[1] * r[1]) + (S[2] * r[2] + S[3] * r[3]);
;                 if ((st & 15) == 15) yo[(size_t)(st - 15) * 64] = tr16_sum(yp, kq);
;                 w = wn; b = bn; k = kn; kk = kkn; r = rn; v = vn;
	v_pk_mul_f32 v[10:11], v[2:3], v[34:35]
	v_pk_fma_f32 v[10:11], v[4:5], v[36:37], v[10:11]
	v_pk_mul_f32 v[14:15], v[2:3], v[184:185]
	v_add_f32_e32 v12, v10, v11
	v_pk_fma_f32 v[14:15], v[4:5], v[186:187], v[14:15]
	v_add_f32_e32 v114, v14, v15
	v_add_f32_dpp v12, v12, v12 quad_perm:[1,0,3,2] row_mask:0xf bank_mask:0xf bound_ctrl:1
	v_pk_mul_f32 v[6:7], v[30:31], v[94:95] op_sel:[0,1] op_sel_hi:[1,1]
	v_pk_mul_f32 v[8:9], v[32:33], v[94:95] op_sel:[0,1] op_sel_hi:[1,1]
	v_add_f32_dpp v12, v12, v12 quad_perm:[2,3,0,1] row_mask:0xf bank_mask:0xf bound_ctrl:1
	v_pk_fma_f32 v[6:7], v[2:3], v[22:23], v[6:7]
	v_pk_fma_f32 v[8:9], v[4:5], v[24:25], v[8:9]
	v_add_f32_dpp v12, v12, v12 row_half_mirror row_mask:0xf bank_mask:0xf bound_ctrl:1
	ds_read_b128 v[156:159], v84 offset:34368
	ds_read_b128 v[144:147], v84 offset:33600
	v_add_f32_dpp v12, v12, v12 row_mirror row_mask:0xf bank_mask:0xf bound_ctrl:1
	ds_read_b128 v[152:155], v84 offset:34112
	ds_read_b128 v[148:151], v84 offset:33856
	ds_read_b128 v[160:163], v84 offset:34624
	v_pk_fma_f32 v[2:3], v[26:27], v[12:13], v[6:7] op_sel_hi:[1,0,1] neg_lo:[0,1,0] neg_hi:[0,1,0]
	v_pk_fma_f32 v[4:5], v[28:29], v[12:13], v[8:9] op_sel_hi:[1,0,1] neg_lo:[0,1,0] neg_hi:[0,1,0]
	s_waitcnt lgkmcnt(5)
	v_pk_mul_f32 v[10:11], v[2:3], v[132:133]
	v_pk_fma_f32 v[10:11], v[4:5], v[134:135], v[10:11]
	v_pk_mul_f32 v[14:15], v[2:3], v[38:39]
	v_add_f32_e32 v12, v10, v11
	v_pk_fma_f32 v[14:15], v[4:5], v[40:41], v[14:15]
	v_add_f32_e32 v115, v14, v15
	v_add_f32_dpp v12, v12, v12 quad_perm:[1,0,3,2] row_mask:0xf bank_mask:0xf bound_ctrl:1
	v_pk_mul_f32 v[6:7], v[128:129], v[116:117] op_sel_hi:[1,0]
	v_pk_mul_f32 v[8:9], v[130:131], v[116:117] op_sel_hi:[1,0]
	v_add_f32_dpp v12, v12, v12 quad_perm:[2,3,0,1] row_mask:0xf bank_mask:0xf bound_ctrl:1
	v_pk_fma_f32 v[6:7], v[2:3], v[120:121], v[6:7]
	v_pk_fma_f32 v[8:9], v[4:5], v[122:123], v[8:9]
	v_add_f32_dpp v12, v12, v12 row_half_mirror row_mask:0xf bank_mask:0xf bound_ctrl:1
	ds_read_b128 v[180:183], v84 offset:35712
	ds_read_b128 v[168:171], v84 offset:34944
	v_add_f32_dpp v12, v12, v12 row_mirror row_mask:0xf bank_mask:0xf bound_ctrl:1
	ds_read_b128 v[176:179], v84 offset:35456
	ds_read_b128 v[172:175], v84 offset:35200
	ds_read_b128 v[184:187], v84 offset:35968
	v_pk_fma_f32 v[2:3], v[124:125], v[12:13], v[6:7] op_sel_hi:[1,0,1] neg_lo:[0,1,0] neg_hi:[0,1,0]
	v_pk_fma_f32 v[4:5], v[126:127], v[12:13], v[8:9] op_sel_hi:[1,0,1] neg_lo:[0,1,0] neg_hi:[0,1,0]
	s_waitcnt lgkmcnt(5)
	v_pk_mul_f32 v[10:11], v[2:3], v[156:157]
	v_pk_fma_f32 v[10:11], v[4:5], v[158:159], v[10:11]
	v_pk_mul_f32 v[14:15], v[2:3], v[136:137]
	v_add_f32_e32 v12, v10, v11
	v_pk_fma_f32 v[14:15], v[4:5], v[138:139], v[14:15]
	v_add_f32_e32 v44, v14, v15
	v_add_f32_dpp v12, v12, v12 quad_perm:[1,0,3,2] row_mask:0xf bank_mask:0xf bound_ctrl:1
	v_add_f32_dpp v108, v108, v108 row_mirror row_mask:0xf bank_mask:0x3 bound_ctrl:1
	v_add_f32_dpp v108, v44, v44 row_mirror row_mask:0xf bank_mask:0xc bound_ctrl:1
	v_add_f32_dpp v12, v12, v12 quad_perm:[2,3,0,1] row_mask:0xf bank_mask:0xf bound_ctrl:1
	v_pk_mul_f32 v[6:7], v[152:153], v[116:117] op_sel:[0,1] op_sel_hi:[1,1]
	v_pk_mul_f32 v[8:9], v[154:155], v[116:117] op_sel:[0,1] op_sel_hi:[1,1]
	v_add_f32_dpp v12, v12, v12 row_half_mirror row_mask:0xf bank_mask:0xf bound_ctrl:1
	v_pk_fma_f32 v[6:7], v[2:3], v[144:145], v[6:7]
	v_pk_fma_f32 v[8:9], v[4:5], v[146:147], v[8:9]
	v_add_f32_dpp v12, v12, v12 row_mirror row_mask:0xf bank_mask:0xf bound_ctrl:1
	ds_read_b128 v[34:37], v84 offset:37056
	ds_read_b128 v[22:25], v84 offset:36288
	ds_read_b128 v[30:33], v84 offset:36800
	ds_read_b128 v[26:29], v84 offset:36544
	ds_read_b128 v[38:41], v84 offset:37312
	v_pk_fma_f32 v[2:3], v[148:149], v[12:13], v[6:7] op_sel_hi:[1,0,1] neg_lo:[0,1,0] neg_hi:[0,1,0]
	v_pk_fma_f32 v[4:5], v[150:151], v[12:13], v[8:9] op_sel_hi:[1,0,1] neg_lo:[0,1,0] neg_hi:[0,1,0]
	s_waitcnt lgkmcnt(5)
	v_pk_mul_f32 v[10:11], v[2:3], v[180:181]
	v_pk_fma_f32 v[10:11], v[4:5], v[182:183], v[10:11]
	v_pk_mul_f32 v[14:15], v[2:3], v[160:161]
	v_add_f32_e32 v12, v10, v11
	v_pk_fma_f32 v[14:15], v[4:5], v[162:163], v[14:15]
	v_add_f32_e32 v44, v14, v15
	v_add_f32_dpp v12, v12, v12 quad_perm:[1,0,3,2] row_mask:0xf bank_mask:0xf bound_ctrl:1
	v_add_f32_dpp v109, v109, v109 row_mirror row_mask:0xf bank_mask:0x3 bound_ctrl:1
	v_add_f32_dpp v109, v44, v44 row_mirror row_mask:0xf bank_mask:0xc bound_ctrl:1
	v_add_f32_dpp v12, v12, v12 quad_perm:[2,3,0,1] row_mask:0xf bank_mask:0xf bound_ctrl:1
	v_pk_mul_f32 v[6:7], v[176:177], v[118:119] op_sel_hi:[1,0]
	v_pk_mul_f32 v[8:9], v[178:179], v[118:119] op_sel_hi:[1,0]
	v_add_f32_dpp v12, v12, v12 row_half_mirror row_mask:0xf bank_mask:0xf bound_ctrl:1
	v_pk_fma_f32 v[6:7], v[2:3], v[168:169], v[6:7]
	v_pk_fma_f32 v[8:9], v[4:5], v[170:171], v[8:9]
	v_add_f32_dpp v12, v12, v12 row_mirror row_mask:0xf bank_mask:0xf bound_ctrl:1
	ds_read_b128 v[132:135], v84 offset:38400
	ds_read_b128 v[120:123], v84 offset:37632
	ds_read_b128 v[128:131], v84 offset:38144
	ds_read_b128 v[92:95], v96 offset:112
	ds_read_b128 v[124:127], v84 offset:37888
	ds_read_b128 v[136:139], v84 offset:38656
	v_pk_fma_f32 v[2:3], v[172:173], v[12:13], v[6:7] op_sel_hi:[1,0,1] neg_lo:[0,1,0] neg_hi:[0,1,0]
	v_pk_fma_f32 v[4:5], v[174:175], v[12:13], v[8:9] op_sel_hi:[1,0,1] neg_lo:[0,1,0] neg_hi:[0,1,0]
	s_waitcnt lgkmcnt(6)
; #define LAS __attribute__((address_space(3)))
; __device__ __forceinline__ float row16_sum(float v) { v += dpp_f<0xB1>(v); v += dpp_f<0x4E>(v); v += dpp_f<0x141>(v); v += dpp_f<0x140>(v); return v; }
; __device__ __forceinline__ void rwkv_scan_unit(LAS unsigned char* lds, const float* Wd, const float* V, const bf16_t* RKKB, float* Yraw, int p, int rg, int tid) {
;     ...
;             for (int st = 0; st < SCAN_CH; ++st) {
;                 f32x4 wn = w, bn = b, kn = k, kkn = kk, rn = r; float vn = v;
;                 if (st + 1 < SCAN_CH) { const int o = (st + 1) * SCAN_STEP_B;
;                     wn = *(LAS const f32x4*)(sl + o); bn = *(LAS const f32x4*)(sl + o + 256); kn = *(LAS const f32x4*)(sl + o + 512); kkn = *(LAS const f32x4*)(sl + o + 768); rn = *(LAS const f32x4*)(sl + o + 1024);
;                     vn = *(LAS const float*)(vl + o); }
;                 float sa = (S[0] * kk[0] + S[1] * kk[1]) + (S[2] * kk[2] + S[3] * kk[3]);
;                 const f32x4 kvt = k * v;
;                 sa = -row16_sum(sa);
;                 S = S * w + (b * sa + kvt);
;                 yp[st & 15] = (S[0] * r[0] + S[1] * r[1]) + (S[2] * r[2] + S[3] * r[3]);
;                 if ((st & 15) == 15) yo[(size_t)(st - 15) * 64] = tr16_sum(yp, kq);
;                 w = wn; b = bn; k = kn; kk = kkn; r = rn; v = vn;
	v_pk_mul_f32 v[10:11], v[2:3], v[34:35]
	v_pk_fma_f32 v[10:11], v[4:5], v[36:37], v[10:11]
	v_pk_mul_f32 v[14:15], v[2:3], v[184:185]
	v_add_f32_e32 v12, v10, v11
	v_pk_fma_f32 v[14:15], v[4:5], v[186:187], v[14:15]
	v_add_f32_e32 v44, v14, v15
	v_add_f32_dpp v12, v12, v12 quad_perm:[1,0,3,2] row_mask:0xf bank_mask:0xf bound_ctrl:1
	v_add_f32_dpp v110, v110, v110 row_mirror row_mask:0xf bank_mask:0x3 bound_ctrl:1
	v_add_f32_dpp v110, v44, v44 row_mirror row_mask:0xf bank_mask:0xc bound_ctrl:1
	v_add_f32_dpp v12, v12, v12 quad_perm:[2,3,0,1] row_mask:0xf bank_mask:0xf bound_ctrl:1
	v_pk_mul_f32 v[6:7], v[30:31], v[118:119] op_sel:[0,1] op_sel_hi:[1,1]
	v_pk_mul_f32 v[8:9], v[32:33], v[118:119] op_sel:[0,1] op_sel_hi:[1,1]
	v_add_f32_dpp v12, v12, v12 row_half_mirror row_mask:0xf bank_mask:0xf bound_ctrl:1
	v_pk_fma_f32 v[6:7], v[2:3], v[22:23], v[6:7]
	v_pk_fma_f32 v[8:9], v[4:5], v[24:25], v[8:9]
	v_add_f32_dpp v12, v12, v12 row_mirror row_mask:0xf bank_mask:0xf bound_ctrl:1
	ds_read_b128 v[156:159], v84 offset:39744
	ds_read_b128 v[144:147], v84 offset:38976
	ds_read_b128 v[152:155], v84 offset:39488
	ds_read_b128 v[148:151], v84 offset:39232
	ds_read_b128 v[160:163], v84 offset:40000
	v_pk_fma_f32 v[2:3], v[26:27], v[12:13], v[6:7] op_sel_hi:[1,0,1] neg_lo:[0,1,0] neg_hi:[0,1,0]
	v_pk_fma_f32 v[4:5], v[28:29], v[12:13], v[8:9] op_sel_hi:[1,0,1] neg_lo:[0,1,0] neg_hi:[0,1,0]
	s_waitcnt lgkmcnt(5)
	v_pk_mul_f32 v[10:11], v[2:3], v[132:133]
	v_pk_fma_f32 v[10:11], v[4:5], v[134:135], v[10:11]
	v_pk_mul_f32 v[14:15], v[2:3], v[38:39]
	v_add_f32_e32 v12, v10, v11
	v_pk_fma_f32 v[14:15], v[4:5], v[40:41], v[14:15]
	v_add_f32_e32 v44, v14, v15
	v_add_f32_dpp v12, v12, v12 quad_perm:[1,0,3,2] row_mask:0xf bank_mask:0xf bound_ctrl:1
	v_add_f32_dpp v111, v111, v111 row_mirror row_mask:0xf bank_mask:0x3 bound_ctrl:1
	v_add_f32_dpp v111, v44, v44 row_mirror row_mask:0xf bank_mask:0xc bound_ctrl:1
	v_add_f32_dpp v12, v12, v12 quad_perm:[2,3,0,1] row_mask:0xf bank_mask:0xf bound_ctrl:1
	v_pk_mul_f32 v[6:7], v[128:129], v[92:93] op_sel_hi:[1,0]
	v_pk_mul_f32 v[8:9], v[130:131], v[92:93] op_sel_hi:[1,0]
	v_add_f32_dpp v12, v12, v12 row_half_mirror row_mask:0xf bank_mask:0xf bound_ctrl:1
	v_pk_fma_f32 v[6:7], v[2:3], v[120:121], v[6:7]
	v_pk_fma_f32 v[8:9], v[4:5], v[122:123], v[8:9]
	v_add_f32_dpp v12, v12, v12 row_mirror row_mask:0xf bank_mask:0xf bound_ctrl:1
	ds_read_b128 v[180:183], v84 offset:41088
	ds_read_b128 v[168:171], v84 offset:40320
	ds_read_b128 v[176:179], v84 offset:40832
	ds_read_b128 v[172:175], v84 offset:40576
	ds_read_b128 v[184:187], v84 offset:41344
	v_pk_fma_f32 v[2:3], v[124:125], v[12:13], v[6:7] op_sel_hi:[1,0,1] neg_lo:[0,1,0] neg_hi:[0,1,0]
	v_pk_fma_f32 v[4:5], v[126:127], v[12:13], v[8:9] op_sel_hi:[1,0,1] neg_lo:[0,1,0] neg_hi:[0,1,0]
	s_waitcnt lgkmcnt(5)
	v_pk_mul_f32 v[10:11], v[2:3], v[156:157]
	v_pk_fma_f32 v[10:11], v[4:5], v[158:159], v[10:11]
	v_pk_mul_f32 v[14:15], v[2:3], v[136:137]
	v_add_f32_e32 v12, v10, v11
	v_pk_fma_f32 v[14:15], v[4:5], v[138:139], v[14:15]
	v_add_f32_e32 v44, v14, v15
	v_add_f32_dpp v12, v12, v12 quad_perm:[1,0,3,2] row_mask:0xf bank_mask:0xf bound_ctrl:1
	v_add_f32_dpp v112, v112, v112 row_mirror row_mask:0xf bank_mask:0x3 bound_ctrl:1
	v_add_f32_dpp v112, v44, v44 row_mirror row_mask:0xf bank_mask:0xc bound_ctrl:1
	v_add_f32_dpp v12, v12, v12 quad_perm:[2,3,0,1] row_mask:0xf bank_mask:0xf bound_ctrl:1
	v_pk_mul_f32 v[6:7], v[152:153], v[92:93] op_sel:[0,1] op_sel_hi:[1,1]
	v_pk_mul_f32 v[8:9], v[154:155], v[92:93] op_sel:[0,1] op_sel_hi:[1,1]
	v_add_f32_dpp v12, v12, v12 row_half_mirror row_mask:0xf bank_mask:0xf bound_ctrl:1
	v_pk_fma_f32 v[6:7], v[2:3], v[144:145], v[6:7]
	v_pk_fma_f32 v[8:9], v[4:5], v[146:147], v[8:9]
	v_add_f32_dpp v12, v12, v12 row_mirror row_mask:0xf bank_mask:0xf bound_ctrl:1
	ds_read_b128 v[34:37], v84 offset:42432
	ds_read_b128 v[22:25], v84 offset:41664
	ds_read_b128 v[30:33], v84 offset:42176
	ds_read_b128 v[26:29], v84 offset:41920
	ds_read_b128 v[38:41], v84 offset:42688
	v_pk_fma_f32 v[2:3], v[148:149], v[12:13], v[6:7] op_sel_hi:[1,0,1] neg_lo:[0,1,0] neg_hi:[0,1,0]
	v_pk_fma_f32 v[4:5], v[150:151], v[12:13], v[8:9] op_sel_hi:[1,0,1] neg_lo:[0,1,0] neg_hi:[0,1,0]
	s_waitcnt lgkmcnt(5)
; #define LAS __attribute__((address_space(3)))
; __device__ __forceinline__ float row16_sum(float v) { v += dpp_f<0xB1>(v); v += dpp_f<0x4E>(v); v += dpp_f<0x141>(v); v += dpp_f<0x140>(v); return v; }
; __device__ __forceinline__ void rwkv_scan_unit(LAS unsigned char* lds, const float* Wd, const float* V, const bf16_t* RKKB, float* Yraw, int p, int rg, int tid) {
;     ...
;             for (int st = 0; st < SCAN_CH; ++st) {
;                 f32x4 wn = w, bn = b, kn = k, kkn = kk, rn = r; float vn = v;
;                 if (st + 1 < SCAN_CH) { const int o = (st + 1) * SCAN_STEP_B;
;                     wn = *(LAS const f32x4*)(sl + o); bn = *(LAS const f32x4*)(sl + o + 256); kn = *(LAS const f32x4*)(sl + o + 512); kkn = *(LAS const f32x4*)(sl + o + 768); rn = *(LAS const f32x4*)(sl + o + 1024);
;                     vn = *(LAS const float*)(vl + o); }
;                 float sa = (S[0] * kk[0] + S[1] * kk[1]) + (S[2] * kk[2] + S[3] * kk[3]);
;                 const f32x4 kvt = k * v;
;                 sa = -row16_sum(sa);
;                 S = S * w + (b * sa + kvt);
;                 yp[st & 15] = (S[0] * r[0] + S[1] * r[1]) + (S[2] * r[2] + S[3] * r[3]);
;                 if ((st & 15) == 15) yo[(size_t)(st - 15) * 64] = tr16_sum(yp, kq);
;                 w = wn; b = bn; k = kn; kk = kkn; r = rn; v = vn;
;             }
;         }
;         __syncthreads();
;     }
	v_pk_mul_f32 v[10:11], v[2:3], v[180:181]
	v_pk_fma_f32 v[10:11], v[4:5], v[182:183], v[10:11]
	v_pk_mul_f32 v[14:15], v[2:3], v[160:161]
	v_add_f32_e32 v12, v10, v11
	v_pk_fma_f32 v[14:15], v[4:5], v[162:163], v[14:15]
	v_add_f32_e32 v44, v14, v15
	v_add_f32_dpp v12, v12, v12 quad_perm:[1,0,3,2] row_mask:0xf bank_mask:0xf bound_ctrl:1
	v_add_f32_dpp v113, v113, v113 row_mirror row_mask:0xf bank_mask:0x3 bound_ctrl:1
	v_add_f32_dpp v113, v44, v44 row_mirror row_mask:0xf bank_mask:0xc bound_ctrl:1
	v_add_f32_dpp v12, v12, v12 quad_perm:[2,3,0,1] row_mask:0xf bank_mask:0xf bound_ctrl:1
	v_pk_mul_f32 v[6:7], v[176:177], v[94:95] op_sel_hi:[1,0]
	v_pk_mul_f32 v[8:9], v[178:179], v[94:95] op_sel_hi:[1,0]
	v_add_f32_dpp v12, v12, v12 row_half_mirror row_mask:0xf bank_mask:0xf bound_ctrl:1
	v_pk_fma_f32 v[6:7], v[2:3], v[168:169], v[6:7]
	v_pk_fma_f32 v[8:9], v[4:5], v[170:171], v[8:9]
	v_add_f32_dpp v12, v12, v12 row_mirror row_mask:0xf bank_mask:0xf bound_ctrl:1
	ds_read_b128 v[132:135], v86 offset:768
	ds_read_b128 v[120:123], v86
	ds_read_b128 v[128:131], v86 offset:512
	ds_read_b128 v[116:119], v97
	ds_read_b128 v[124:127], v86 offset:256
	ds_read_b128 v[136:139], v86 offset:1024
	v_pk_fma_f32 v[2:3], v[172:173], v[12:13], v[6:7] op_sel_hi:[1,0,1] neg_lo:[0,1,0] neg_hi:[0,1,0]
	v_pk_fma_f32 v[4:5], v[174:175], v[12:13], v[8:9] op_sel_hi:[1,0,1] neg_lo:[0,1,0] neg_hi:[0,1,0]
	s_waitcnt lgkmcnt(6)
	v_pk_mul_f32 v[10:11], v[2:3], v[34:35]
	v_pk_fma_f32 v[10:11], v[4:5], v[36:37], v[10:11]
	v_pk_mul_f32 v[14:15], v[2:3], v[184:185]
	v_add_f32_e32 v12, v10, v11
	v_pk_fma_f32 v[14:15], v[4:5], v[186:187], v[14:15]
	v_add_f32_e32 v44, v14, v15
	v_add_f32_dpp v12, v12, v12 quad_perm:[1,0,3,2] row_mask:0xf bank_mask:0xf bound_ctrl:1
	v_add_f32_dpp v114, v114, v114 row_mirror row_mask:0xf bank_mask:0x3 bound_ctrl:1
	v_add_f32_dpp v114, v44, v44 row_mirror row_mask:0xf bank_mask:0xc bound_ctrl:1
	v_add_f32_dpp v12, v12, v12 quad_perm:[2,3,0,1] row_mask:0xf bank_mask:0xf bound_ctrl:1
	v_pk_mul_f32 v[6:7], v[30:31], v[94:95] op_sel:[0,1] op_sel_hi:[1,1]
	v_pk_mul_f32 v[8:9], v[32:33], v[94:95] op_sel:[0,1] op_sel_hi:[1,1]
	v_add_f32_dpp v12, v12, v12 row_half_mirror row_mask:0xf bank_mask:0xf bound_ctrl:1
	v_pk_fma_f32 v[6:7], v[2:3], v[22:23], v[6:7]
	v_pk_fma_f32 v[8:9], v[4:5], v[24:25], v[8:9]
	v_add_f32_dpp v12, v12, v12 row_mirror row_mask:0xf bank_mask:0xf bound_ctrl:1
	ds_read_b128 v[156:159], v86 offset:2112
	ds_read_b128 v[144:147], v86 offset:1344
	ds_read_b128 v[152:155], v86 offset:1856
	ds_read_b128 v[148:151], v86 offset:1600
	ds_read_b128 v[160:163], v86 offset:2368
	v_pk_fma_f32 v[2:3], v[26:27], v[12:13], v[6:7] op_sel_hi:[1,0,1] neg_lo:[0,1,0] neg_hi:[0,1,0]
	v_pk_fma_f32 v[4:5], v[28:29], v[12:13], v[8:9] op_sel_hi:[1,0,1] neg_lo:[0,1,0] neg_hi:[0,1,0]
	v_pk_mul_f32 v[14:15], v[2:3], v[38:39]
	v_pk_fma_f32 v[14:15], v[4:5], v[40:41], v[14:15]
	v_add_f32_e32 v44, v14, v15
	v_add_f32_dpp v115, v115, v115 row_mirror row_mask:0xf bank_mask:0x3 bound_ctrl:1
	s_nop 0
	v_add_f32_dpp v115, v44, v44 row_mirror row_mask:0xf bank_mask:0xc bound_ctrl:1
	v_add_f32_dpp v108, v108, v108 row_half_mirror row_mask:0xf bank_mask:0x5 bound_ctrl:1
	v_add_f32_dpp v108, v112, v112 row_half_mirror row_mask:0xf bank_mask:0xa bound_ctrl:1
	v_add_f32_dpp v109, v109, v109 row_half_mirror row_mask:0xf bank_mask:0x5 bound_ctrl:1
	v_add_f32_dpp v109, v113, v113 row_half_mirror row_mask:0xf bank_mask:0xa bound_ctrl:1
	v_add_f32_dpp v110, v110, v110 row_half_mirror row_mask:0xf bank_mask:0x5 bound_ctrl:1
	v_add_f32_dpp v110, v114, v114 row_half_mirror row_mask:0xf bank_mask:0xa bound_ctrl:1
	v_add_f32_dpp v111, v111, v111 row_half_mirror row_mask:0xf bank_mask:0x5 bound_ctrl:1
	v_add_f32_dpp v111, v115, v115 row_half_mirror row_mask:0xf bank_mask:0xa bound_ctrl:1
	v_cndmask_b32_e64 v16, v110, v108, s[8:9]
	v_cndmask_b32_e64 v17, v108, v110, s[8:9]
	s_nop 1
	v_add_f32_dpp v16, v17, v16 quad_perm:[2,3,0,1] row_mask:0xf bank_mask:0xf bound_ctrl:1
	v_cndmask_b32_e64 v18, v111, v109, s[8:9]
	v_cndmask_b32_e64 v19, v109, v111, s[8:9]
	s_nop 1
	v_add_f32_dpp v18, v19, v18 quad_perm:[2,3,0,1] row_mask:0xf bank_mask:0xf bound_ctrl:1
	v_cndmask_b32_e64 v17, v18, v16, s[10:11]
	v_cndmask_b32_e64 v19, v16, v18, s[10:11]
	s_nop 1
	v_add_f32_dpp v17, v19, v17 quad_perm:[1,0,3,2] row_mask:0xf bank_mask:0xf bound_ctrl:1
	global_store_dword v[90:91], v17, off
	s_add_i32 s22, s22, 1
	s_mov_b64 s[68:69], 0x2000
	s_mov_b32 s18, s19
	s_add_i32 s19, s19, 0xa800
	s_cmp_eq_u32 s19, 0x1f800
	s_cselect_b32 s19, 0, s19
	v_lshl_add_u64 v[88:89], v[88:89], 0, s[68:69]
	v_lshl_add_u64 v[90:91], v[90:91], 0, s[68:69]
	s_cmpk_eq_i32 s22, 0x80
	s_barrier
	s_cbranch_scc1 .LBB0_370
	s_branch .Lscan_top
